# GEMM K-loops: per-cluster setprio toggles removed (no priority changes in the loops)
# baseline (speedup 1.0000x reference)
.LBB0_243:
	s_cmpk_eq_i32 s4, 0x700
	v_lshl_add_u64 v[170:171], v[152:153], 0, s[4:5]
	s_mov_b64 s[6:7], 0x4280100
	v_lshl_add_u64 v[170:171], v[170:171], 0, s[6:7]
	s_cselect_b64 vcc, -1, 0
	s_add_i32 s6, 0, 0x10000
	v_cndmask_b32_e32 v245, v171, v147, vcc
	v_add_u32_e32 v171, s6, v174
	ds_read_b128 v[176:179], v171
	ds_read_b128 v[180:183], v171 offset:1024
	ds_read_b128 v[184:187], v171 offset:2048
	ds_read_b128 v[188:191], v171 offset:3072
	v_cndmask_b32_e32 v244, v170, v146, vcc
	v_lshl_add_u64 v[170:171], v[168:169], 0, s[4:5]
	v_cndmask_b32_e32 v171, v171, v145, vcc
	v_cndmask_b32_e32 v170, v170, v144, vcc
	v_lshl_add_u64 v[228:229], v[148:149], 0, s[4:5]
	s_add_i32 m0, s26, 0xc000
	ds_read_b128 v[192:195], v175
	ds_read_b128 v[196:199], v175 offset:1024
	ds_read_b128 v[200:203], v175 offset:2048
	ds_read_b128 v[204:207], v175 offset:3072
	ds_read_b128 v[210:213], v175 offset:4096
	ds_read_b128 v[214:217], v175 offset:5120
	ds_read_b128 v[218:221], v175 offset:6144
	ds_read_b128 v[222:225], v175 offset:7168
	global_load_lds_dwordx4 v[228:229], off
	v_lshl_add_u64 v[228:229], v[150:151], 0, s[4:5]
	s_add_i32 m0, s26, 0xe000
	s_nop 0
	global_load_lds_dwordx4 v[228:229], off
	s_waitcnt lgkmcnt(8)
	s_barrier
	s_waitcnt lgkmcnt(7)
	v_mfma_f32_16x16x32_bf16 v[126:129], v[176:179], v[192:195], v[126:129]
	v_mfma_f32_16x16x32_bf16 v[122:125], v[184:187], v[192:195], v[122:125]
	s_waitcnt lgkmcnt(5)
	v_mfma_f32_16x16x32_bf16 v[118:121], v[176:179], v[200:203], v[118:121]
	v_mfma_f32_16x16x32_bf16 v[114:117], v[184:187], v[200:203], v[114:117]
	s_waitcnt lgkmcnt(3)
	v_mfma_f32_16x16x32_bf16 v[110:113], v[176:179], v[210:213], v[110:113]
	v_mfma_f32_16x16x32_bf16 v[106:109], v[184:187], v[210:213], v[106:109]
	s_waitcnt lgkmcnt(1)
	v_mfma_f32_16x16x32_bf16 v[102:105], v[176:179], v[218:221], v[102:105]
	v_mfma_f32_16x16x32_bf16 v[98:101], v[184:187], v[218:221], v[98:101]
	v_mfma_f32_16x16x32_bf16 v[126:129], v[180:183], v[196:199], v[126:129]
	v_mfma_f32_16x16x32_bf16 v[122:125], v[188:191], v[196:199], v[122:125]
	v_mfma_f32_16x16x32_bf16 v[118:121], v[180:183], v[204:207], v[118:121]
	v_mfma_f32_16x16x32_bf16 v[114:117], v[188:191], v[204:207], v[114:117]
	v_mfma_f32_16x16x32_bf16 v[110:113], v[180:183], v[214:217], v[110:113]
	v_mfma_f32_16x16x32_bf16 v[106:109], v[188:191], v[214:217], v[106:109]
	s_waitcnt lgkmcnt(0)
	v_mfma_f32_16x16x32_bf16 v[102:105], v[180:183], v[222:225], v[102:105]
	v_mfma_f32_16x16x32_bf16 v[98:101], v[188:191], v[222:225], v[98:101]
	s_barrier
	s_add_i32 s7, 0, 0x14000
	s_add_i32 s6, s6, s13
	v_add_u32_e32 v208, s7, v174
	v_lshl_add_u64 v[246:247], v[170:171], 0, v[132:133]
	s_mov_b32 m0, s6
	ds_read_b128 v[228:231], v208
	ds_read_b128 v[232:235], v208 offset:1024
	ds_read_b128 v[236:239], v208 offset:2048
	ds_read_b128 v[240:243], v208 offset:3072
	global_load_lds_dwordx4 v[246:247], off
	v_lshl_add_u64 v[248:249], v[170:171], 0, v[142:143]
	s_add_i32 m0, s6, 0x2000
	s_nop 0
	global_load_lds_dwordx4 v[248:249], off
	s_barrier
	s_waitcnt lgkmcnt(3)
	v_mfma_f32_16x16x32_bf16 v[94:97], v[228:231], v[192:195], v[94:97]
	s_waitcnt lgkmcnt(1)
	v_mfma_f32_16x16x32_bf16 v[90:93], v[236:239], v[192:195], v[90:93]
	v_mfma_f32_16x16x32_bf16 v[86:89], v[228:231], v[200:203], v[86:89]
	v_mfma_f32_16x16x32_bf16 v[82:85], v[236:239], v[200:203], v[82:85]
	v_mfma_f32_16x16x32_bf16 v[78:81], v[228:231], v[210:213], v[78:81]
	v_mfma_f32_16x16x32_bf16 v[74:77], v[236:239], v[210:213], v[74:77]
	v_mfma_f32_16x16x32_bf16 v[70:73], v[228:231], v[218:221], v[70:73]
	v_mfma_f32_16x16x32_bf16 v[66:69], v[236:239], v[218:221], v[66:69]
	v_mfma_f32_16x16x32_bf16 v[94:97], v[232:235], v[196:199], v[94:97]
	s_waitcnt lgkmcnt(0)
	v_mfma_f32_16x16x32_bf16 v[90:93], v[240:243], v[196:199], v[90:93]
	v_mfma_f32_16x16x32_bf16 v[86:89], v[232:235], v[204:207], v[86:89]
	v_mfma_f32_16x16x32_bf16 v[82:85], v[240:243], v[204:207], v[82:85]
	v_mfma_f32_16x16x32_bf16 v[78:81], v[232:235], v[214:217], v[78:81]
	v_mfma_f32_16x16x32_bf16 v[74:77], v[240:243], v[214:217], v[74:77]
	v_mfma_f32_16x16x32_bf16 v[70:73], v[232:235], v[222:225], v[70:73]
	v_mfma_f32_16x16x32_bf16 v[66:69], v[240:243], v[222:225], v[66:69]
	s_mov_b32 m0, s26
	v_lshl_add_u64 v[250:251], v[244:245], 0, v[132:133]
	s_barrier
	ds_read_b128 v[192:195], v175 offset:16384
	ds_read_b128 v[196:199], v175 offset:17408
	ds_read_b128 v[200:203], v175 offset:18432
	ds_read_b128 v[204:207], v175 offset:19456
	ds_read_b128 v[210:213], v175 offset:20480
	ds_read_b128 v[214:217], v175 offset:21504
	ds_read_b128 v[218:221], v175 offset:22528
	ds_read_b128 v[222:225], v175 offset:23552
	global_load_lds_dwordx4 v[250:251], off
	v_lshl_add_u64 v[252:253], v[244:245], 0, v[142:143]
	s_mov_b32 m0, s41
	s_nop 0
	global_load_lds_dwordx4 v[252:253], off
	s_barrier
	s_waitcnt lgkmcnt(7)
	v_mfma_f32_16x16x32_bf16 v[62:65], v[176:179], v[192:195], v[62:65]
	v_mfma_f32_16x16x32_bf16 v[58:61], v[184:187], v[192:195], v[58:61]
	s_waitcnt lgkmcnt(5)
	v_mfma_f32_16x16x32_bf16 v[54:57], v[176:179], v[200:203], v[54:57]
	v_mfma_f32_16x16x32_bf16 v[50:53], v[184:187], v[200:203], v[50:53]
	s_waitcnt lgkmcnt(3)
	v_mfma_f32_16x16x32_bf16 v[46:49], v[176:179], v[210:213], v[46:49]
	v_mfma_f32_16x16x32_bf16 v[42:45], v[184:187], v[210:213], v[42:45]
	s_waitcnt lgkmcnt(1)
	v_mfma_f32_16x16x32_bf16 v[38:41], v[176:179], v[218:221], v[38:41]
	v_mfma_f32_16x16x32_bf16 v[34:37], v[184:187], v[218:221], v[34:37]
	v_mfma_f32_16x16x32_bf16 v[62:65], v[180:183], v[196:199], v[62:65]
	v_mfma_f32_16x16x32_bf16 v[58:61], v[188:191], v[196:199], v[58:61]
	v_mfma_f32_16x16x32_bf16 v[54:57], v[180:183], v[204:207], v[54:57]
	v_mfma_f32_16x16x32_bf16 v[50:53], v[188:191], v[204:207], v[50:53]
	v_mfma_f32_16x16x32_bf16 v[46:49], v[180:183], v[214:217], v[46:49]
	v_mfma_f32_16x16x32_bf16 v[42:45], v[188:191], v[214:217], v[42:45]
	s_waitcnt lgkmcnt(0)
	v_mfma_f32_16x16x32_bf16 v[38:41], v[180:183], v[222:225], v[38:41]
	v_mfma_f32_16x16x32_bf16 v[34:37], v[188:191], v[222:225], v[34:37]
	s_barrier
	v_lshl_add_u64 v[176:177], v[170:171], 0, s[28:29]
	s_add_i32 s6, s7, s13
	v_lshl_add_u64 v[178:179], v[176:177], 0, v[132:133]
	s_mov_b32 m0, s6
	v_lshl_add_u64 v[176:177], v[176:177], 0, v[142:143]
	global_load_lds_dwordx4 v[178:179], off
	s_add_i32 m0, s6, 0x2000
	s_nop 0
	global_load_lds_dwordx4 v[176:177], off
	s_waitcnt vmcnt(6)
	s_barrier
	v_mfma_f32_16x16x32_bf16 v[30:33], v[228:231], v[192:195], v[30:33]
	v_mfma_f32_16x16x32_bf16 v[26:29], v[236:239], v[192:195], v[26:29]
	v_mfma_f32_16x16x32_bf16 v[22:25], v[228:231], v[200:203], v[22:25]
	v_mfma_f32_16x16x32_bf16 v[18:21], v[236:239], v[200:203], v[18:21]
	v_mfma_f32_16x16x32_bf16 v[14:17], v[228:231], v[210:213], v[14:17]
	v_mfma_f32_16x16x32_bf16 v[10:13], v[236:239], v[210:213], v[10:13]
	v_mfma_f32_16x16x32_bf16 v[6:9], v[228:231], v[218:221], v[6:9]
	v_mfma_f32_16x16x32_bf16 v[2:5], v[236:239], v[218:221], v[2:5]
	v_mfma_f32_16x16x32_bf16 v[30:33], v[232:235], v[196:199], v[30:33]
	v_mfma_f32_16x16x32_bf16 v[26:29], v[240:243], v[196:199], v[26:29]
	v_mfma_f32_16x16x32_bf16 v[22:25], v[232:235], v[204:207], v[22:25]
	v_mfma_f32_16x16x32_bf16 v[18:21], v[240:243], v[204:207], v[18:21]
	v_mfma_f32_16x16x32_bf16 v[14:17], v[232:235], v[214:217], v[14:17]
	v_mfma_f32_16x16x32_bf16 v[10:13], v[240:243], v[214:217], v[10:13]
	v_mfma_f32_16x16x32_bf16 v[6:9], v[232:235], v[222:225], v[6:9]
	v_mfma_f32_16x16x32_bf16 v[2:5], v[240:243], v[222:225], v[2:5]
	s_add_i32 s6, 0, 0x18000
	v_add_u32_e32 v188, s6, v174
	s_barrier
	ds_read_b128 v[176:179], v188
	ds_read_b128 v[180:183], v188 offset:1024
	ds_read_b128 v[184:187], v188 offset:2048
	ds_read_b128 v[188:191], v188 offset:3072
	v_lshl_add_u64 v[228:229], v[244:245], 0, s[28:29]
	s_mov_b32 m0, s42
	v_lshl_add_u64 v[230:231], v[228:229], 0, v[132:133]
	ds_read_b128 v[192:195], v175 offset:32768
	ds_read_b128 v[196:199], v175 offset:33792
	ds_read_b128 v[200:203], v175 offset:34816
	ds_read_b128 v[204:207], v175 offset:35840
	ds_read_b128 v[210:213], v175 offset:36864
	ds_read_b128 v[214:217], v175 offset:37888
	ds_read_b128 v[218:221], v175 offset:38912
	ds_read_b128 v[222:225], v175 offset:39936
	global_load_lds_dwordx4 v[230:231], off
	v_lshl_add_u64 v[228:229], v[228:229], 0, v[142:143]
	s_mov_b32 m0, s43
	s_nop 0
	global_load_lds_dwordx4 v[228:229], off
	s_waitcnt lgkmcnt(8)
	s_barrier
	s_waitcnt lgkmcnt(7)
	v_mfma_f32_16x16x32_bf16 v[126:129], v[176:179], v[192:195], v[126:129]
	v_mfma_f32_16x16x32_bf16 v[122:125], v[184:187], v[192:195], v[122:125]
	s_waitcnt lgkmcnt(5)
	v_mfma_f32_16x16x32_bf16 v[118:121], v[176:179], v[200:203], v[118:121]
	v_mfma_f32_16x16x32_bf16 v[114:117], v[184:187], v[200:203], v[114:117]
	s_waitcnt lgkmcnt(3)
	v_mfma_f32_16x16x32_bf16 v[110:113], v[176:179], v[210:213], v[110:113]
	v_mfma_f32_16x16x32_bf16 v[106:109], v[184:187], v[210:213], v[106:109]
	s_waitcnt lgkmcnt(1)
	v_mfma_f32_16x16x32_bf16 v[102:105], v[176:179], v[218:221], v[102:105]
	v_mfma_f32_16x16x32_bf16 v[98:101], v[184:187], v[218:221], v[98:101]
	v_mfma_f32_16x16x32_bf16 v[126:129], v[180:183], v[196:199], v[126:129]
	v_mfma_f32_16x16x32_bf16 v[122:125], v[188:191], v[196:199], v[122:125]
	v_mfma_f32_16x16x32_bf16 v[118:121], v[180:183], v[204:207], v[118:121]
	v_mfma_f32_16x16x32_bf16 v[114:117], v[188:191], v[204:207], v[114:117]
	v_mfma_f32_16x16x32_bf16 v[110:113], v[180:183], v[214:217], v[110:113]
	v_mfma_f32_16x16x32_bf16 v[106:109], v[188:191], v[214:217], v[106:109]
	s_waitcnt lgkmcnt(0)
	v_mfma_f32_16x16x32_bf16 v[102:105], v[180:183], v[222:225], v[102:105]
	v_mfma_f32_16x16x32_bf16 v[98:101], v[188:191], v[222:225], v[98:101]
	s_barrier
	s_add_i32 s7, 0, 0x1c000
	s_add_i32 s6, s6, s13
	v_add_u32_e32 v208, s7, v174
	v_lshl_add_u64 v[244:245], v[246:247], 0, s[30:31]
	s_mov_b32 m0, s6
	ds_read_b128 v[228:231], v208
	ds_read_b128 v[232:235], v208 offset:1024
	ds_read_b128 v[236:239], v208 offset:2048
	ds_read_b128 v[240:243], v208 offset:3072
	global_load_lds_dwordx4 v[244:245], off
	v_lshl_add_u64 v[244:245], v[248:249], 0, s[30:31]
	s_add_i32 m0, s6, 0x2000
	s_nop 0
	global_load_lds_dwordx4 v[244:245], off
	s_barrier
	s_waitcnt lgkmcnt(3)
	v_mfma_f32_16x16x32_bf16 v[94:97], v[228:231], v[192:195], v[94:97]
	s_waitcnt lgkmcnt(1)
	v_mfma_f32_16x16x32_bf16 v[90:93], v[236:239], v[192:195], v[90:93]
	v_mfma_f32_16x16x32_bf16 v[86:89], v[228:231], v[200:203], v[86:89]
	v_mfma_f32_16x16x32_bf16 v[82:85], v[236:239], v[200:203], v[82:85]
	v_mfma_f32_16x16x32_bf16 v[78:81], v[228:231], v[210:213], v[78:81]
	v_mfma_f32_16x16x32_bf16 v[74:77], v[236:239], v[210:213], v[74:77]
	v_mfma_f32_16x16x32_bf16 v[70:73], v[228:231], v[218:221], v[70:73]
	v_mfma_f32_16x16x32_bf16 v[66:69], v[236:239], v[218:221], v[66:69]
	v_mfma_f32_16x16x32_bf16 v[94:97], v[232:235], v[196:199], v[94:97]
	s_waitcnt lgkmcnt(0)
	v_mfma_f32_16x16x32_bf16 v[90:93], v[240:243], v[196:199], v[90:93]
	v_mfma_f32_16x16x32_bf16 v[86:89], v[232:235], v[204:207], v[86:89]
	v_mfma_f32_16x16x32_bf16 v[82:85], v[240:243], v[204:207], v[82:85]
	v_mfma_f32_16x16x32_bf16 v[78:81], v[232:235], v[214:217], v[78:81]
	v_mfma_f32_16x16x32_bf16 v[74:77], v[240:243], v[214:217], v[74:77]
	v_mfma_f32_16x16x32_bf16 v[70:73], v[232:235], v[222:225], v[70:73]
	v_mfma_f32_16x16x32_bf16 v[66:69], v[240:243], v[222:225], v[66:69]
	s_mov_b32 m0, s44
	v_lshl_add_u64 v[244:245], v[250:251], 0, s[30:31]
	s_barrier
	ds_read_b128 v[192:195], v175 offset:49152
	ds_read_b128 v[196:199], v175 offset:50176
	ds_read_b128 v[200:203], v175 offset:51200
	ds_read_b128 v[204:207], v175 offset:52224
	ds_read_b128 v[210:213], v175 offset:53248
	ds_read_b128 v[214:217], v175 offset:54272
	ds_read_b128 v[218:221], v175 offset:55296
	ds_read_b128 v[222:225], v175 offset:56320
	global_load_lds_dwordx4 v[244:245], off
	v_lshl_add_u64 v[244:245], v[252:253], 0, s[30:31]
	s_mov_b32 m0, s45
	s_nop 0
	global_load_lds_dwordx4 v[244:245], off
	s_barrier
	s_waitcnt lgkmcnt(7)
	v_mfma_f32_16x16x32_bf16 v[62:65], v[176:179], v[192:195], v[62:65]
	v_mfma_f32_16x16x32_bf16 v[58:61], v[184:187], v[192:195], v[58:61]
	s_waitcnt lgkmcnt(5)
	v_mfma_f32_16x16x32_bf16 v[54:57], v[176:179], v[200:203], v[54:57]
	v_mfma_f32_16x16x32_bf16 v[50:53], v[184:187], v[200:203], v[50:53]
	s_waitcnt lgkmcnt(3)
	v_mfma_f32_16x16x32_bf16 v[46:49], v[176:179], v[210:213], v[46:49]
	v_mfma_f32_16x16x32_bf16 v[42:45], v[184:187], v[210:213], v[42:45]
	s_waitcnt lgkmcnt(1)
	v_mfma_f32_16x16x32_bf16 v[38:41], v[176:179], v[218:221], v[38:41]
	v_mfma_f32_16x16x32_bf16 v[34:37], v[184:187], v[218:221], v[34:37]
	v_mfma_f32_16x16x32_bf16 v[62:65], v[180:183], v[196:199], v[62:65]
	v_mfma_f32_16x16x32_bf16 v[58:61], v[188:191], v[196:199], v[58:61]
	v_mfma_f32_16x16x32_bf16 v[54:57], v[180:183], v[204:207], v[54:57]
	v_mfma_f32_16x16x32_bf16 v[50:53], v[188:191], v[204:207], v[50:53]
	v_mfma_f32_16x16x32_bf16 v[46:49], v[180:183], v[214:217], v[46:49]
	v_mfma_f32_16x16x32_bf16 v[42:45], v[188:191], v[214:217], v[42:45]
	s_waitcnt lgkmcnt(0)
	v_mfma_f32_16x16x32_bf16 v[38:41], v[180:183], v[222:225], v[38:41]
	v_mfma_f32_16x16x32_bf16 v[34:37], v[188:191], v[222:225], v[34:37]
	s_barrier
	v_lshl_add_u64 v[170:171], v[170:171], 0, s[34:35]
	s_add_i32 s6, s7, s13
	v_lshl_add_u64 v[176:177], v[170:171], 0, v[132:133]
	s_mov_b32 m0, s6
	v_lshl_add_u64 v[170:171], v[170:171], 0, v[142:143]
	global_load_lds_dwordx4 v[176:177], off
	s_add_i32 m0, s6, 0x2000
	s_nop 0
	global_load_lds_dwordx4 v[170:171], off
	s_waitcnt vmcnt(6)
	s_barrier
	v_mfma_f32_16x16x32_bf16 v[30:33], v[228:231], v[192:195], v[30:33]
	v_mfma_f32_16x16x32_bf16 v[26:29], v[236:239], v[192:195], v[26:29]
	v_mfma_f32_16x16x32_bf16 v[22:25], v[228:231], v[200:203], v[22:25]
	v_mfma_f32_16x16x32_bf16 v[18:21], v[236:239], v[200:203], v[18:21]
	v_mfma_f32_16x16x32_bf16 v[14:17], v[228:231], v[210:213], v[14:17]
	v_mfma_f32_16x16x32_bf16 v[10:13], v[236:239], v[210:213], v[10:13]
	v_mfma_f32_16x16x32_bf16 v[6:9], v[228:231], v[218:221], v[6:9]
	v_mfma_f32_16x16x32_bf16 v[2:5], v[236:239], v[218:221], v[2:5]
	v_mfma_f32_16x16x32_bf16 v[30:33], v[232:235], v[196:199], v[30:33]
	v_mfma_f32_16x16x32_bf16 v[26:29], v[240:243], v[196:199], v[26:29]
	v_mfma_f32_16x16x32_bf16 v[22:25], v[232:235], v[204:207], v[22:25]
	v_mfma_f32_16x16x32_bf16 v[18:21], v[240:243], v[204:207], v[18:21]
	v_mfma_f32_16x16x32_bf16 v[14:17], v[232:235], v[214:217], v[14:17]
	v_mfma_f32_16x16x32_bf16 v[10:13], v[240:243], v[214:217], v[10:13]
	v_mfma_f32_16x16x32_bf16 v[6:9], v[232:235], v[222:225], v[6:9]
	v_mfma_f32_16x16x32_bf16 v[2:5], v[240:243], v[222:225], v[2:5]
	s_add_i32 s46, s46, 2
	s_add_u32 s4, s4, 0x100
	s_addc_u32 s5, s5, 0
	s_cmp_lt_u32 s46, 14
	s_barrier
	s_cbranch_scc1 .LBB0_243
	s_waitcnt vmcnt(0)
	s_cmpk_gt_u32 s12, 0xff
	s_cbranch_scc1 .LBB0_246
	s_barrier

.LBB0_756:
	s_add_u32 s42, s6, 0xfbd20080
	s_addc_u32 s43, s7, -1
	s_cmp_lg_u32 s41, 20
	s_cselect_b32 s43, s43, 0
	s_cselect_b32 s42, s42, 0
	s_add_i32 s44, 0, 0x10000
	v_add_u32_e32 v152, s44, v168
	ds_read_b128 v[170:173], v152
	ds_read_b128 v[174:177], v152 offset:1024
	ds_read_b128 v[178:181], v152 offset:2048
	ds_read_b128 v[182:185], v152 offset:3072
	v_lshl_add_u64 v[206:207], v[146:147], 0, s[42:43]
	v_lshl_add_u64 v[152:153], v[144:145], 0, s[42:43]
	v_lshl_add_u64 v[222:223], v[148:149], 0, s[6:7]
	s_add_i32 m0, s34, 0xc000
	ds_read_b128 v[186:189], v169
	ds_read_b128 v[190:193], v169 offset:1024
	ds_read_b128 v[194:197], v169 offset:2048
	ds_read_b128 v[198:201], v169 offset:3072
	ds_read_b128 v[202:205], v169 offset:4096
	ds_read_b128 v[210:213], v169 offset:5120
	ds_read_b128 v[214:217], v169 offset:6144
	ds_read_b128 v[218:221], v169 offset:7168
	global_load_lds_dwordx4 v[222:223], off
	v_lshl_add_u64 v[222:223], v[150:151], 0, s[6:7]
	s_add_i32 m0, s34, 0xe000
	s_nop 0
	global_load_lds_dwordx4 v[222:223], off
	s_waitcnt lgkmcnt(8)
	s_barrier
	s_waitcnt lgkmcnt(7)
	v_mfma_f32_16x16x32_bf16 v[126:129], v[170:173], v[186:189], v[126:129]
	v_mfma_f32_16x16x32_bf16 v[122:125], v[178:181], v[186:189], v[122:125]
	s_waitcnt lgkmcnt(5)
	v_mfma_f32_16x16x32_bf16 v[118:121], v[170:173], v[194:197], v[118:121]
	v_mfma_f32_16x16x32_bf16 v[114:117], v[178:181], v[194:197], v[114:117]
	s_waitcnt lgkmcnt(3)
	v_mfma_f32_16x16x32_bf16 v[110:113], v[170:173], v[202:205], v[110:113]
	v_mfma_f32_16x16x32_bf16 v[106:109], v[178:181], v[202:205], v[106:109]
	s_waitcnt lgkmcnt(1)
	v_mfma_f32_16x16x32_bf16 v[102:105], v[170:173], v[214:217], v[102:105]
	v_mfma_f32_16x16x32_bf16 v[98:101], v[178:181], v[214:217], v[98:101]
	v_mfma_f32_16x16x32_bf16 v[126:129], v[174:177], v[190:193], v[126:129]
	v_mfma_f32_16x16x32_bf16 v[122:125], v[182:185], v[190:193], v[122:125]
	v_mfma_f32_16x16x32_bf16 v[118:121], v[174:177], v[198:201], v[118:121]
	v_mfma_f32_16x16x32_bf16 v[114:117], v[182:185], v[198:201], v[114:117]
	v_mfma_f32_16x16x32_bf16 v[110:113], v[174:177], v[210:213], v[110:113]
	v_mfma_f32_16x16x32_bf16 v[106:109], v[182:185], v[210:213], v[106:109]
	s_waitcnt lgkmcnt(0)
	v_mfma_f32_16x16x32_bf16 v[102:105], v[174:177], v[218:221], v[102:105]
	v_mfma_f32_16x16x32_bf16 v[98:101], v[182:185], v[218:221], v[98:101]
	s_barrier
	s_add_i32 s42, 0, 0x14000
	s_add_i32 s43, s44, s33
	v_add_u32_e32 v208, s42, v168
	v_lshl_add_u64 v[240:241], v[152:153], 0, v[134:135]
	s_mov_b32 m0, s43
	ds_read_b128 v[222:225], v208
	ds_read_b128 v[228:231], v208 offset:1024
	ds_read_b128 v[232:235], v208 offset:2048
	ds_read_b128 v[236:239], v208 offset:3072
	global_load_lds_dwordx4 v[240:241], off
	v_lshl_add_u64 v[242:243], v[152:153], 0, v[142:143]
	s_add_i32 m0, s43, 0x2000
	s_nop 0
	global_load_lds_dwordx4 v[242:243], off
	s_barrier
	s_waitcnt lgkmcnt(3)
	v_mfma_f32_16x16x32_bf16 v[94:97], v[222:225], v[186:189], v[94:97]
	s_waitcnt lgkmcnt(1)
	v_mfma_f32_16x16x32_bf16 v[90:93], v[232:235], v[186:189], v[90:93]
	v_mfma_f32_16x16x32_bf16 v[86:89], v[222:225], v[194:197], v[86:89]
	v_mfma_f32_16x16x32_bf16 v[82:85], v[232:235], v[194:197], v[82:85]
	v_mfma_f32_16x16x32_bf16 v[78:81], v[222:225], v[202:205], v[78:81]
	v_mfma_f32_16x16x32_bf16 v[74:77], v[232:235], v[202:205], v[74:77]
	v_mfma_f32_16x16x32_bf16 v[70:73], v[222:225], v[214:217], v[70:73]
	v_mfma_f32_16x16x32_bf16 v[66:69], v[232:235], v[214:217], v[66:69]
	v_mfma_f32_16x16x32_bf16 v[94:97], v[228:231], v[190:193], v[94:97]
	s_waitcnt lgkmcnt(0)
	v_mfma_f32_16x16x32_bf16 v[90:93], v[236:239], v[190:193], v[90:93]
	v_mfma_f32_16x16x32_bf16 v[86:89], v[228:231], v[198:201], v[86:89]
	v_mfma_f32_16x16x32_bf16 v[82:85], v[236:239], v[198:201], v[82:85]
	v_mfma_f32_16x16x32_bf16 v[78:81], v[228:231], v[210:213], v[78:81]
	v_mfma_f32_16x16x32_bf16 v[74:77], v[236:239], v[210:213], v[74:77]
	v_mfma_f32_16x16x32_bf16 v[70:73], v[228:231], v[218:221], v[70:73]
	v_mfma_f32_16x16x32_bf16 v[66:69], v[236:239], v[218:221], v[66:69]
	s_mov_b32 m0, s34
	v_lshl_add_u64 v[244:245], v[206:207], 0, v[134:135]
	s_barrier
	ds_read_b128 v[186:189], v169 offset:16384
	ds_read_b128 v[190:193], v169 offset:17408
	ds_read_b128 v[194:197], v169 offset:18432
	ds_read_b128 v[198:201], v169 offset:19456
	ds_read_b128 v[202:205], v169 offset:20480
	ds_read_b128 v[210:213], v169 offset:21504
	ds_read_b128 v[214:217], v169 offset:22528
	ds_read_b128 v[218:221], v169 offset:23552
	global_load_lds_dwordx4 v[244:245], off
	v_lshl_add_u64 v[246:247], v[206:207], 0, v[142:143]
	s_mov_b32 m0, s35
	s_nop 0
	global_load_lds_dwordx4 v[246:247], off
	s_barrier
	s_waitcnt lgkmcnt(7)
	v_mfma_f32_16x16x32_bf16 v[62:65], v[170:173], v[186:189], v[62:65]
	v_mfma_f32_16x16x32_bf16 v[58:61], v[178:181], v[186:189], v[58:61]
	s_waitcnt lgkmcnt(5)
	v_mfma_f32_16x16x32_bf16 v[54:57], v[170:173], v[194:197], v[54:57]
	v_mfma_f32_16x16x32_bf16 v[50:53], v[178:181], v[194:197], v[50:53]
	s_waitcnt lgkmcnt(3)
	v_mfma_f32_16x16x32_bf16 v[46:49], v[170:173], v[202:205], v[46:49]
	v_mfma_f32_16x16x32_bf16 v[42:45], v[178:181], v[202:205], v[42:45]
	s_waitcnt lgkmcnt(1)
	v_mfma_f32_16x16x32_bf16 v[38:41], v[170:173], v[214:217], v[38:41]
	v_mfma_f32_16x16x32_bf16 v[34:37], v[178:181], v[214:217], v[34:37]
	v_mfma_f32_16x16x32_bf16 v[62:65], v[174:177], v[190:193], v[62:65]
	v_mfma_f32_16x16x32_bf16 v[58:61], v[182:185], v[190:193], v[58:61]
	v_mfma_f32_16x16x32_bf16 v[54:57], v[174:177], v[198:201], v[54:57]
	v_mfma_f32_16x16x32_bf16 v[50:53], v[182:185], v[198:201], v[50:53]
	v_mfma_f32_16x16x32_bf16 v[46:49], v[174:177], v[210:213], v[46:49]
	v_mfma_f32_16x16x32_bf16 v[42:45], v[182:185], v[210:213], v[42:45]
	s_waitcnt lgkmcnt(0)
	v_mfma_f32_16x16x32_bf16 v[38:41], v[174:177], v[218:221], v[38:41]
	v_mfma_f32_16x16x32_bf16 v[34:37], v[182:185], v[218:221], v[34:37]
	s_barrier
	v_lshl_add_u64 v[170:171], v[152:153], 0, s[14:15]
	s_add_i32 s42, s42, s33
	v_lshl_add_u64 v[172:173], v[170:171], 0, v[134:135]
	s_mov_b32 m0, s42
	v_lshl_add_u64 v[170:171], v[170:171], 0, v[142:143]
	global_load_lds_dwordx4 v[172:173], off
	s_add_i32 m0, s42, 0x2000
	s_nop 0
	global_load_lds_dwordx4 v[170:171], off
	s_waitcnt vmcnt(6)
	s_barrier
	v_mfma_f32_16x16x32_bf16 v[30:33], v[222:225], v[186:189], v[30:33]
	v_mfma_f32_16x16x32_bf16 v[26:29], v[232:235], v[186:189], v[26:29]
	v_mfma_f32_16x16x32_bf16 v[22:25], v[222:225], v[194:197], v[22:25]
	v_mfma_f32_16x16x32_bf16 v[18:21], v[232:235], v[194:197], v[18:21]
	v_mfma_f32_16x16x32_bf16 v[14:17], v[222:225], v[202:205], v[14:17]
	v_mfma_f32_16x16x32_bf16 v[10:13], v[232:235], v[202:205], v[10:13]
	v_mfma_f32_16x16x32_bf16 v[6:9], v[222:225], v[214:217], v[6:9]
	v_mfma_f32_16x16x32_bf16 v[2:5], v[232:235], v[214:217], v[2:5]
	v_mfma_f32_16x16x32_bf16 v[30:33], v[228:231], v[190:193], v[30:33]
	v_mfma_f32_16x16x32_bf16 v[26:29], v[236:239], v[190:193], v[26:29]
	v_mfma_f32_16x16x32_bf16 v[22:25], v[228:231], v[198:201], v[22:25]
	v_mfma_f32_16x16x32_bf16 v[18:21], v[236:239], v[198:201], v[18:21]
	v_mfma_f32_16x16x32_bf16 v[14:17], v[228:231], v[210:213], v[14:17]
	v_mfma_f32_16x16x32_bf16 v[10:13], v[236:239], v[210:213], v[10:13]
	v_mfma_f32_16x16x32_bf16 v[6:9], v[228:231], v[218:221], v[6:9]
	v_mfma_f32_16x16x32_bf16 v[2:5], v[236:239], v[218:221], v[2:5]
	s_add_i32 s42, 0, 0x18000
	v_add_u32_e32 v182, s42, v168
	s_barrier
	ds_read_b128 v[170:173], v182
	ds_read_b128 v[174:177], v182 offset:1024
	ds_read_b128 v[178:181], v182 offset:2048
	ds_read_b128 v[182:185], v182 offset:3072
	v_lshl_add_u64 v[206:207], v[206:207], 0, s[14:15]
	s_mov_b32 m0, s37
	v_lshl_add_u64 v[222:223], v[206:207], 0, v[134:135]
	ds_read_b128 v[186:189], v169 offset:32768
	ds_read_b128 v[190:193], v169 offset:33792
	ds_read_b128 v[194:197], v169 offset:34816
	ds_read_b128 v[198:201], v169 offset:35840
	ds_read_b128 v[202:205], v169 offset:36864
	ds_read_b128 v[210:213], v169 offset:37888
	ds_read_b128 v[214:217], v169 offset:38912
	ds_read_b128 v[218:221], v169 offset:39936
	global_load_lds_dwordx4 v[222:223], off
	v_lshl_add_u64 v[206:207], v[206:207], 0, v[142:143]
	s_mov_b32 m0, s38
	s_nop 0
	global_load_lds_dwordx4 v[206:207], off
	s_waitcnt lgkmcnt(8)
	s_barrier
	s_waitcnt lgkmcnt(7)
	v_mfma_f32_16x16x32_bf16 v[126:129], v[170:173], v[186:189], v[126:129]
	v_mfma_f32_16x16x32_bf16 v[122:125], v[178:181], v[186:189], v[122:125]
	s_waitcnt lgkmcnt(5)
	v_mfma_f32_16x16x32_bf16 v[118:121], v[170:173], v[194:197], v[118:121]
	v_mfma_f32_16x16x32_bf16 v[114:117], v[178:181], v[194:197], v[114:117]
	s_waitcnt lgkmcnt(3)
	v_mfma_f32_16x16x32_bf16 v[110:113], v[170:173], v[202:205], v[110:113]
	v_mfma_f32_16x16x32_bf16 v[106:109], v[178:181], v[202:205], v[106:109]
	s_waitcnt lgkmcnt(1)
	v_mfma_f32_16x16x32_bf16 v[102:105], v[170:173], v[214:217], v[102:105]
	v_mfma_f32_16x16x32_bf16 v[98:101], v[178:181], v[214:217], v[98:101]
	v_mfma_f32_16x16x32_bf16 v[126:129], v[174:177], v[190:193], v[126:129]
	v_mfma_f32_16x16x32_bf16 v[122:125], v[182:185], v[190:193], v[122:125]
	v_mfma_f32_16x16x32_bf16 v[118:121], v[174:177], v[198:201], v[118:121]
	v_mfma_f32_16x16x32_bf16 v[114:117], v[182:185], v[198:201], v[114:117]
	v_mfma_f32_16x16x32_bf16 v[110:113], v[174:177], v[210:213], v[110:113]
	v_mfma_f32_16x16x32_bf16 v[106:109], v[182:185], v[210:213], v[106:109]
	s_waitcnt lgkmcnt(0)
	v_mfma_f32_16x16x32_bf16 v[102:105], v[174:177], v[218:221], v[102:105]
	v_mfma_f32_16x16x32_bf16 v[98:101], v[182:185], v[218:221], v[98:101]
	s_barrier
	s_add_i32 s43, 0, 0x1c000
	v_add_u32_e32 v206, s43, v168
	s_add_i32 s42, s42, s33
	ds_read_b128 v[222:225], v206
	ds_read_b128 v[228:231], v206 offset:1024
	ds_read_b128 v[232:235], v206 offset:2048
	ds_read_b128 v[236:239], v206 offset:3072
	v_lshl_add_u64 v[206:207], v[240:241], 0, s[16:17]
	s_mov_b32 m0, s42
	s_nop 0
	global_load_lds_dwordx4 v[206:207], off
	v_lshl_add_u64 v[206:207], v[242:243], 0, s[16:17]
	s_add_i32 m0, s42, 0x2000
	s_nop 0
	global_load_lds_dwordx4 v[206:207], off
	s_barrier
	s_waitcnt lgkmcnt(3)
	v_mfma_f32_16x16x32_bf16 v[94:97], v[222:225], v[186:189], v[94:97]
	s_waitcnt lgkmcnt(1)
	v_mfma_f32_16x16x32_bf16 v[90:93], v[232:235], v[186:189], v[90:93]
	v_mfma_f32_16x16x32_bf16 v[86:89], v[222:225], v[194:197], v[86:89]
	v_mfma_f32_16x16x32_bf16 v[82:85], v[232:235], v[194:197], v[82:85]
	v_mfma_f32_16x16x32_bf16 v[78:81], v[222:225], v[202:205], v[78:81]
	v_mfma_f32_16x16x32_bf16 v[74:77], v[232:235], v[202:205], v[74:77]
	v_mfma_f32_16x16x32_bf16 v[70:73], v[222:225], v[214:217], v[70:73]
	v_mfma_f32_16x16x32_bf16 v[66:69], v[232:235], v[214:217], v[66:69]
	v_mfma_f32_16x16x32_bf16 v[94:97], v[228:231], v[190:193], v[94:97]
	s_waitcnt lgkmcnt(0)
	v_mfma_f32_16x16x32_bf16 v[90:93], v[236:239], v[190:193], v[90:93]
	v_mfma_f32_16x16x32_bf16 v[86:89], v[228:231], v[198:201], v[86:89]
	v_mfma_f32_16x16x32_bf16 v[82:85], v[236:239], v[198:201], v[82:85]
	v_mfma_f32_16x16x32_bf16 v[78:81], v[228:231], v[210:213], v[78:81]
	v_mfma_f32_16x16x32_bf16 v[74:77], v[236:239], v[210:213], v[74:77]
	v_mfma_f32_16x16x32_bf16 v[70:73], v[228:231], v[218:221], v[70:73]
	v_mfma_f32_16x16x32_bf16 v[66:69], v[236:239], v[218:221], v[66:69]
	s_mov_b32 m0, s39
	v_lshl_add_u64 v[206:207], v[244:245], 0, s[16:17]
	s_barrier
	ds_read_b128 v[186:189], v169 offset:49152
	ds_read_b128 v[190:193], v169 offset:50176
	ds_read_b128 v[194:197], v169 offset:51200
	ds_read_b128 v[198:201], v169 offset:52224
	ds_read_b128 v[202:205], v169 offset:53248
	ds_read_b128 v[210:213], v169 offset:54272
	ds_read_b128 v[214:217], v169 offset:55296
	ds_read_b128 v[218:221], v169 offset:56320
	global_load_lds_dwordx4 v[206:207], off
	v_lshl_add_u64 v[206:207], v[246:247], 0, s[16:17]
	s_mov_b32 m0, s40
	s_nop 0
	global_load_lds_dwordx4 v[206:207], off
	s_barrier
	s_waitcnt lgkmcnt(7)
	v_mfma_f32_16x16x32_bf16 v[62:65], v[170:173], v[186:189], v[62:65]
	v_mfma_f32_16x16x32_bf16 v[58:61], v[178:181], v[186:189], v[58:61]
	s_waitcnt lgkmcnt(5)
	v_mfma_f32_16x16x32_bf16 v[54:57], v[170:173], v[194:197], v[54:57]
	v_mfma_f32_16x16x32_bf16 v[50:53], v[178:181], v[194:197], v[50:53]
	s_waitcnt lgkmcnt(3)
	v_mfma_f32_16x16x32_bf16 v[46:49], v[170:173], v[202:205], v[46:49]
	v_mfma_f32_16x16x32_bf16 v[42:45], v[178:181], v[202:205], v[42:45]
	s_waitcnt lgkmcnt(1)
	v_mfma_f32_16x16x32_bf16 v[38:41], v[170:173], v[214:217], v[38:41]
	v_mfma_f32_16x16x32_bf16 v[34:37], v[178:181], v[214:217], v[34:37]
	v_mfma_f32_16x16x32_bf16 v[62:65], v[174:177], v[190:193], v[62:65]
	v_mfma_f32_16x16x32_bf16 v[58:61], v[182:185], v[190:193], v[58:61]
	v_mfma_f32_16x16x32_bf16 v[54:57], v[174:177], v[198:201], v[54:57]
	v_mfma_f32_16x16x32_bf16 v[50:53], v[182:185], v[198:201], v[50:53]
	v_mfma_f32_16x16x32_bf16 v[46:49], v[174:177], v[210:213], v[46:49]
	v_mfma_f32_16x16x32_bf16 v[42:45], v[182:185], v[210:213], v[42:45]
	s_waitcnt lgkmcnt(0)
	v_mfma_f32_16x16x32_bf16 v[38:41], v[174:177], v[218:221], v[38:41]
	v_mfma_f32_16x16x32_bf16 v[34:37], v[182:185], v[218:221], v[34:37]
	s_barrier
	v_lshl_add_u64 v[152:153], v[152:153], 0, s[18:19]
	s_add_i32 s42, s43, s33
	v_lshl_add_u64 v[170:171], v[152:153], 0, v[134:135]
	s_mov_b32 m0, s42
	v_lshl_add_u64 v[152:153], v[152:153], 0, v[142:143]
	global_load_lds_dwordx4 v[170:171], off
	s_add_i32 m0, s42, 0x2000
	s_nop 0
	global_load_lds_dwordx4 v[152:153], off
	s_waitcnt vmcnt(6)
	s_barrier
	v_mfma_f32_16x16x32_bf16 v[30:33], v[222:225], v[186:189], v[30:33]
	v_mfma_f32_16x16x32_bf16 v[26:29], v[232:235], v[186:189], v[26:29]
	v_mfma_f32_16x16x32_bf16 v[22:25], v[222:225], v[194:197], v[22:25]
	v_mfma_f32_16x16x32_bf16 v[18:21], v[232:235], v[194:197], v[18:21]
	v_mfma_f32_16x16x32_bf16 v[14:17], v[222:225], v[202:205], v[14:17]
	v_mfma_f32_16x16x32_bf16 v[10:13], v[232:235], v[202:205], v[10:13]
	v_mfma_f32_16x16x32_bf16 v[6:9], v[222:225], v[214:217], v[6:9]
	v_mfma_f32_16x16x32_bf16 v[2:5], v[232:235], v[214:217], v[2:5]
	v_mfma_f32_16x16x32_bf16 v[30:33], v[228:231], v[190:193], v[30:33]
	v_mfma_f32_16x16x32_bf16 v[26:29], v[236:239], v[190:193], v[26:29]
	v_mfma_f32_16x16x32_bf16 v[22:25], v[228:231], v[198:201], v[22:25]
	v_mfma_f32_16x16x32_bf16 v[18:21], v[236:239], v[198:201], v[18:21]
	v_mfma_f32_16x16x32_bf16 v[14:17], v[228:231], v[210:213], v[14:17]
	v_mfma_f32_16x16x32_bf16 v[10:13], v[236:239], v[210:213], v[10:13]
	v_mfma_f32_16x16x32_bf16 v[6:9], v[228:231], v[218:221], v[6:9]
	v_mfma_f32_16x16x32_bf16 v[2:5], v[236:239], v[218:221], v[2:5]
	s_add_i32 s41, s41, 2
	s_add_u32 s6, s6, 0x100
	s_addc_u32 s7, s7, 0
	s_cmp_lt_u32 s41, 22
	s_barrier
	s_cbranch_scc1 .LBB0_756
	s_waitcnt vmcnt(0)
	s_cmpk_gt_u32 s31, 0xff
	s_cbranch_scc1 .LBB0_759
	s_barrier

.LBB0_914:
	s_cmpk_eq_i32 s6, 0x700
	v_lshl_add_u64 v[170:171], v[150:151], 0, s[6:7]
	v_lshl_add_u64 v[170:171], v[170:171], 0, s[20:21]
	s_cselect_b64 vcc, -1, 0
	s_add_i32 s9, 0, 0x10000
	v_cndmask_b32_e32 v245, v171, v149, vcc
	v_add_u32_e32 v171, s9, v173
	ds_read_b128 v[176:179], v171
	ds_read_b128 v[180:183], v171 offset:1024
	ds_read_b128 v[184:187], v171 offset:2048
	ds_read_b128 v[188:191], v171 offset:3072
	v_cndmask_b32_e32 v244, v170, v148, vcc
	v_lshl_add_u64 v[170:171], v[168:169], 0, s[6:7]
	v_cndmask_b32_e32 v171, v171, v147, vcc
	v_cndmask_b32_e32 v170, v170, v146, vcc
	v_lshl_add_u64 v[228:229], v[152:153], 0, s[6:7]
	s_add_i32 m0, s34, 0xc000
	ds_read_b128 v[192:195], v174
	ds_read_b128 v[196:199], v174 offset:1024
	ds_read_b128 v[200:203], v174 offset:2048
	ds_read_b128 v[204:207], v174 offset:3072
	ds_read_b128 v[210:213], v174 offset:4096
	ds_read_b128 v[214:217], v174 offset:5120
	ds_read_b128 v[218:221], v174 offset:6144
	ds_read_b128 v[222:225], v174 offset:7168
	global_load_lds_dwordx4 v[228:229], off
	v_lshl_add_u64 v[228:229], v[166:167], 0, s[6:7]
	s_add_i32 m0, s34, 0xe000
	s_nop 0
	global_load_lds_dwordx4 v[228:229], off
	s_waitcnt lgkmcnt(8)
	s_barrier
	s_waitcnt lgkmcnt(7)
	v_mfma_f32_16x16x32_bf16 v[126:129], v[176:179], v[192:195], v[126:129]
	v_mfma_f32_16x16x32_bf16 v[122:125], v[184:187], v[192:195], v[122:125]
	s_waitcnt lgkmcnt(5)
	v_mfma_f32_16x16x32_bf16 v[118:121], v[176:179], v[200:203], v[118:121]
	v_mfma_f32_16x16x32_bf16 v[114:117], v[184:187], v[200:203], v[114:117]
	s_waitcnt lgkmcnt(3)
	v_mfma_f32_16x16x32_bf16 v[110:113], v[176:179], v[210:213], v[110:113]
	v_mfma_f32_16x16x32_bf16 v[106:109], v[184:187], v[210:213], v[106:109]
	s_waitcnt lgkmcnt(1)
	v_mfma_f32_16x16x32_bf16 v[102:105], v[176:179], v[218:221], v[102:105]
	v_mfma_f32_16x16x32_bf16 v[98:101], v[184:187], v[218:221], v[98:101]
	v_mfma_f32_16x16x32_bf16 v[126:129], v[180:183], v[196:199], v[126:129]
	v_mfma_f32_16x16x32_bf16 v[122:125], v[188:191], v[196:199], v[122:125]
	v_mfma_f32_16x16x32_bf16 v[118:121], v[180:183], v[204:207], v[118:121]
	v_mfma_f32_16x16x32_bf16 v[114:117], v[188:191], v[204:207], v[114:117]
	v_mfma_f32_16x16x32_bf16 v[110:113], v[180:183], v[214:217], v[110:113]
	v_mfma_f32_16x16x32_bf16 v[106:109], v[188:191], v[214:217], v[106:109]
	s_waitcnt lgkmcnt(0)
	v_mfma_f32_16x16x32_bf16 v[102:105], v[180:183], v[222:225], v[102:105]
	v_mfma_f32_16x16x32_bf16 v[98:101], v[188:191], v[222:225], v[98:101]
	s_barrier
	s_add_i32 s57, 0, 0x14000
	s_add_i32 s9, s9, s39
	v_add_u32_e32 v175, s57, v173
	v_lshl_add_u64 v[246:247], v[170:171], 0, v[134:135]
	s_mov_b32 m0, s9
	ds_read_b128 v[228:231], v175
	ds_read_b128 v[232:235], v175 offset:1024
	ds_read_b128 v[236:239], v175 offset:2048
	ds_read_b128 v[240:243], v175 offset:3072
	global_load_lds_dwordx4 v[246:247], off
	v_lshl_add_u64 v[248:249], v[170:171], 0, v[144:145]
	s_add_i32 m0, s9, 0x2000
	s_nop 0
	global_load_lds_dwordx4 v[248:249], off
	s_barrier
	s_waitcnt lgkmcnt(3)
	v_mfma_f32_16x16x32_bf16 v[94:97], v[228:231], v[192:195], v[94:97]
	s_waitcnt lgkmcnt(1)
	v_mfma_f32_16x16x32_bf16 v[90:93], v[236:239], v[192:195], v[90:93]
	v_mfma_f32_16x16x32_bf16 v[86:89], v[228:231], v[200:203], v[86:89]
	v_mfma_f32_16x16x32_bf16 v[82:85], v[236:239], v[200:203], v[82:85]
	v_mfma_f32_16x16x32_bf16 v[78:81], v[228:231], v[210:213], v[78:81]
	v_mfma_f32_16x16x32_bf16 v[74:77], v[236:239], v[210:213], v[74:77]
	v_mfma_f32_16x16x32_bf16 v[70:73], v[228:231], v[218:221], v[70:73]
	v_mfma_f32_16x16x32_bf16 v[66:69], v[236:239], v[218:221], v[66:69]
	v_mfma_f32_16x16x32_bf16 v[94:97], v[232:235], v[196:199], v[94:97]
	s_waitcnt lgkmcnt(0)
	v_mfma_f32_16x16x32_bf16 v[90:93], v[240:243], v[196:199], v[90:93]
	v_mfma_f32_16x16x32_bf16 v[86:89], v[232:235], v[204:207], v[86:89]
	v_mfma_f32_16x16x32_bf16 v[82:85], v[240:243], v[204:207], v[82:85]
	v_mfma_f32_16x16x32_bf16 v[78:81], v[232:235], v[214:217], v[78:81]
	v_mfma_f32_16x16x32_bf16 v[74:77], v[240:243], v[214:217], v[74:77]
	v_mfma_f32_16x16x32_bf16 v[70:73], v[232:235], v[222:225], v[70:73]
	v_mfma_f32_16x16x32_bf16 v[66:69], v[240:243], v[222:225], v[66:69]
	s_mov_b32 m0, s34
	v_lshl_add_u64 v[250:251], v[244:245], 0, v[134:135]
	s_barrier
	ds_read_b128 v[192:195], v174 offset:16384
	ds_read_b128 v[196:199], v174 offset:17408
	ds_read_b128 v[200:203], v174 offset:18432
	ds_read_b128 v[204:207], v174 offset:19456
	ds_read_b128 v[210:213], v174 offset:20480
	ds_read_b128 v[214:217], v174 offset:21504
	ds_read_b128 v[218:221], v174 offset:22528
	ds_read_b128 v[222:225], v174 offset:23552
	global_load_lds_dwordx4 v[250:251], off
	v_lshl_add_u64 v[252:253], v[244:245], 0, v[144:145]
	s_mov_b32 m0, s41
	s_nop 0
	global_load_lds_dwordx4 v[252:253], off
	s_barrier
	s_waitcnt lgkmcnt(7)
	v_mfma_f32_16x16x32_bf16 v[62:65], v[176:179], v[192:195], v[62:65]
	v_mfma_f32_16x16x32_bf16 v[58:61], v[184:187], v[192:195], v[58:61]
	s_waitcnt lgkmcnt(5)
	v_mfma_f32_16x16x32_bf16 v[54:57], v[176:179], v[200:203], v[54:57]
	v_mfma_f32_16x16x32_bf16 v[50:53], v[184:187], v[200:203], v[50:53]
	s_waitcnt lgkmcnt(3)
	v_mfma_f32_16x16x32_bf16 v[46:49], v[176:179], v[210:213], v[46:49]
	v_mfma_f32_16x16x32_bf16 v[42:45], v[184:187], v[210:213], v[42:45]
	s_waitcnt lgkmcnt(1)
	v_mfma_f32_16x16x32_bf16 v[38:41], v[176:179], v[218:221], v[38:41]
	v_mfma_f32_16x16x32_bf16 v[34:37], v[184:187], v[218:221], v[34:37]
	v_mfma_f32_16x16x32_bf16 v[62:65], v[180:183], v[196:199], v[62:65]
	v_mfma_f32_16x16x32_bf16 v[58:61], v[188:191], v[196:199], v[58:61]
	v_mfma_f32_16x16x32_bf16 v[54:57], v[180:183], v[204:207], v[54:57]
	v_mfma_f32_16x16x32_bf16 v[50:53], v[188:191], v[204:207], v[50:53]
	v_mfma_f32_16x16x32_bf16 v[46:49], v[180:183], v[214:217], v[46:49]
	v_mfma_f32_16x16x32_bf16 v[42:45], v[188:191], v[214:217], v[42:45]
	s_waitcnt lgkmcnt(0)
	v_mfma_f32_16x16x32_bf16 v[38:41], v[180:183], v[222:225], v[38:41]
	v_mfma_f32_16x16x32_bf16 v[34:37], v[188:191], v[222:225], v[34:37]
	s_barrier
	v_lshl_add_u64 v[176:177], v[170:171], 0, s[10:11]
	s_add_i32 s9, s57, s39
	v_lshl_add_u64 v[178:179], v[176:177], 0, v[134:135]
	s_mov_b32 m0, s9
	v_lshl_add_u64 v[176:177], v[176:177], 0, v[144:145]
	global_load_lds_dwordx4 v[178:179], off
	s_add_i32 m0, s9, 0x2000
	s_nop 0
	global_load_lds_dwordx4 v[176:177], off
	s_waitcnt vmcnt(6)
	s_barrier
	v_mfma_f32_16x16x32_bf16 v[30:33], v[228:231], v[192:195], v[30:33]
	v_mfma_f32_16x16x32_bf16 v[26:29], v[236:239], v[192:195], v[26:29]
	v_mfma_f32_16x16x32_bf16 v[22:25], v[228:231], v[200:203], v[22:25]
	v_mfma_f32_16x16x32_bf16 v[18:21], v[236:239], v[200:203], v[18:21]
	v_mfma_f32_16x16x32_bf16 v[14:17], v[228:231], v[210:213], v[14:17]
	v_mfma_f32_16x16x32_bf16 v[10:13], v[236:239], v[210:213], v[10:13]
	v_mfma_f32_16x16x32_bf16 v[6:9], v[228:231], v[218:221], v[6:9]
	v_mfma_f32_16x16x32_bf16 v[2:5], v[236:239], v[218:221], v[2:5]
	v_mfma_f32_16x16x32_bf16 v[30:33], v[232:235], v[196:199], v[30:33]
	v_mfma_f32_16x16x32_bf16 v[26:29], v[240:243], v[196:199], v[26:29]
	v_mfma_f32_16x16x32_bf16 v[22:25], v[232:235], v[204:207], v[22:25]
	v_mfma_f32_16x16x32_bf16 v[18:21], v[240:243], v[204:207], v[18:21]
	v_mfma_f32_16x16x32_bf16 v[14:17], v[232:235], v[214:217], v[14:17]
	v_mfma_f32_16x16x32_bf16 v[10:13], v[240:243], v[214:217], v[10:13]
	v_mfma_f32_16x16x32_bf16 v[6:9], v[232:235], v[222:225], v[6:9]
	v_mfma_f32_16x16x32_bf16 v[2:5], v[240:243], v[222:225], v[2:5]
	s_add_i32 s9, 0, 0x18000
	v_add_u32_e32 v175, s9, v173
	s_barrier
	ds_read_b128 v[176:179], v175
	ds_read_b128 v[180:183], v175 offset:1024
	ds_read_b128 v[184:187], v175 offset:2048
	ds_read_b128 v[188:191], v175 offset:3072
	v_lshl_add_u64 v[228:229], v[244:245], 0, s[10:11]
	s_mov_b32 m0, s42
	v_lshl_add_u64 v[230:231], v[228:229], 0, v[134:135]
	ds_read_b128 v[192:195], v174 offset:32768
	ds_read_b128 v[196:199], v174 offset:33792
	ds_read_b128 v[200:203], v174 offset:34816
	ds_read_b128 v[204:207], v174 offset:35840
	ds_read_b128 v[210:213], v174 offset:36864
	ds_read_b128 v[214:217], v174 offset:37888
	ds_read_b128 v[218:221], v174 offset:38912
	ds_read_b128 v[222:225], v174 offset:39936
	global_load_lds_dwordx4 v[230:231], off
	v_lshl_add_u64 v[228:229], v[228:229], 0, v[144:145]
	s_mov_b32 m0, s43
	s_nop 0
	global_load_lds_dwordx4 v[228:229], off
	s_waitcnt lgkmcnt(8)
	s_barrier
	s_waitcnt lgkmcnt(7)
	v_mfma_f32_16x16x32_bf16 v[126:129], v[176:179], v[192:195], v[126:129]
	v_mfma_f32_16x16x32_bf16 v[122:125], v[184:187], v[192:195], v[122:125]
	s_waitcnt lgkmcnt(5)
	v_mfma_f32_16x16x32_bf16 v[118:121], v[176:179], v[200:203], v[118:121]
	v_mfma_f32_16x16x32_bf16 v[114:117], v[184:187], v[200:203], v[114:117]
	s_waitcnt lgkmcnt(3)
	v_mfma_f32_16x16x32_bf16 v[110:113], v[176:179], v[210:213], v[110:113]
	v_mfma_f32_16x16x32_bf16 v[106:109], v[184:187], v[210:213], v[106:109]
	s_waitcnt lgkmcnt(1)
	v_mfma_f32_16x16x32_bf16 v[102:105], v[176:179], v[218:221], v[102:105]
	v_mfma_f32_16x16x32_bf16 v[98:101], v[184:187], v[218:221], v[98:101]
	v_mfma_f32_16x16x32_bf16 v[126:129], v[180:183], v[196:199], v[126:129]
	v_mfma_f32_16x16x32_bf16 v[122:125], v[188:191], v[196:199], v[122:125]
	v_mfma_f32_16x16x32_bf16 v[118:121], v[180:183], v[204:207], v[118:121]
	v_mfma_f32_16x16x32_bf16 v[114:117], v[188:191], v[204:207], v[114:117]
	v_mfma_f32_16x16x32_bf16 v[110:113], v[180:183], v[214:217], v[110:113]
	v_mfma_f32_16x16x32_bf16 v[106:109], v[188:191], v[214:217], v[106:109]
	s_waitcnt lgkmcnt(0)
	v_mfma_f32_16x16x32_bf16 v[102:105], v[180:183], v[222:225], v[102:105]
	v_mfma_f32_16x16x32_bf16 v[98:101], v[188:191], v[222:225], v[98:101]
	s_barrier
	s_add_i32 s57, 0, 0x1c000
	s_add_i32 s9, s9, s39
	v_add_u32_e32 v175, s57, v173
	v_lshl_add_u64 v[244:245], v[246:247], 0, s[16:17]
	s_mov_b32 m0, s9
	ds_read_b128 v[228:231], v175
	ds_read_b128 v[232:235], v175 offset:1024
	ds_read_b128 v[236:239], v175 offset:2048
	ds_read_b128 v[240:243], v175 offset:3072
	global_load_lds_dwordx4 v[244:245], off
	v_lshl_add_u64 v[244:245], v[248:249], 0, s[16:17]
	s_add_i32 m0, s9, 0x2000
	s_nop 0
	global_load_lds_dwordx4 v[244:245], off
	s_barrier
	s_waitcnt lgkmcnt(3)
	v_mfma_f32_16x16x32_bf16 v[94:97], v[228:231], v[192:195], v[94:97]
	s_waitcnt lgkmcnt(1)
	v_mfma_f32_16x16x32_bf16 v[90:93], v[236:239], v[192:195], v[90:93]
	v_mfma_f32_16x16x32_bf16 v[86:89], v[228:231], v[200:203], v[86:89]
	v_mfma_f32_16x16x32_bf16 v[82:85], v[236:239], v[200:203], v[82:85]
	v_mfma_f32_16x16x32_bf16 v[78:81], v[228:231], v[210:213], v[78:81]
	v_mfma_f32_16x16x32_bf16 v[74:77], v[236:239], v[210:213], v[74:77]
	v_mfma_f32_16x16x32_bf16 v[70:73], v[228:231], v[218:221], v[70:73]
	v_mfma_f32_16x16x32_bf16 v[66:69], v[236:239], v[218:221], v[66:69]
	v_mfma_f32_16x16x32_bf16 v[94:97], v[232:235], v[196:199], v[94:97]
	s_waitcnt lgkmcnt(0)
	v_mfma_f32_16x16x32_bf16 v[90:93], v[240:243], v[196:199], v[90:93]
	v_mfma_f32_16x16x32_bf16 v[86:89], v[232:235], v[204:207], v[86:89]
	v_mfma_f32_16x16x32_bf16 v[82:85], v[240:243], v[204:207], v[82:85]
	v_mfma_f32_16x16x32_bf16 v[78:81], v[232:235], v[214:217], v[78:81]
	v_mfma_f32_16x16x32_bf16 v[74:77], v[240:243], v[214:217], v[74:77]
	v_mfma_f32_16x16x32_bf16 v[70:73], v[232:235], v[222:225], v[70:73]
	v_mfma_f32_16x16x32_bf16 v[66:69], v[240:243], v[222:225], v[66:69]
	s_mov_b32 m0, s55
	v_lshl_add_u64 v[244:245], v[250:251], 0, s[16:17]
	s_barrier
	ds_read_b128 v[192:195], v174 offset:49152
	ds_read_b128 v[196:199], v174 offset:50176
	ds_read_b128 v[200:203], v174 offset:51200
	ds_read_b128 v[204:207], v174 offset:52224
	ds_read_b128 v[210:213], v174 offset:53248
	ds_read_b128 v[214:217], v174 offset:54272
	ds_read_b128 v[218:221], v174 offset:55296
	ds_read_b128 v[222:225], v174 offset:56320
	global_load_lds_dwordx4 v[244:245], off
	v_lshl_add_u64 v[244:245], v[252:253], 0, s[16:17]
	s_mov_b32 m0, s56
	s_nop 0
	global_load_lds_dwordx4 v[244:245], off
	s_barrier
	s_waitcnt lgkmcnt(7)
	v_mfma_f32_16x16x32_bf16 v[62:65], v[176:179], v[192:195], v[62:65]
	v_mfma_f32_16x16x32_bf16 v[58:61], v[184:187], v[192:195], v[58:61]
	s_waitcnt lgkmcnt(5)
	v_mfma_f32_16x16x32_bf16 v[54:57], v[176:179], v[200:203], v[54:57]
	v_mfma_f32_16x16x32_bf16 v[50:53], v[184:187], v[200:203], v[50:53]
	s_waitcnt lgkmcnt(3)
	v_mfma_f32_16x16x32_bf16 v[46:49], v[176:179], v[210:213], v[46:49]
	v_mfma_f32_16x16x32_bf16 v[42:45], v[184:187], v[210:213], v[42:45]
	s_waitcnt lgkmcnt(1)
	v_mfma_f32_16x16x32_bf16 v[38:41], v[176:179], v[218:221], v[38:41]
	v_mfma_f32_16x16x32_bf16 v[34:37], v[184:187], v[218:221], v[34:37]
	v_mfma_f32_16x16x32_bf16 v[62:65], v[180:183], v[196:199], v[62:65]
	v_mfma_f32_16x16x32_bf16 v[58:61], v[188:191], v[196:199], v[58:61]
	v_mfma_f32_16x16x32_bf16 v[54:57], v[180:183], v[204:207], v[54:57]
	v_mfma_f32_16x16x32_bf16 v[50:53], v[188:191], v[204:207], v[50:53]
	v_mfma_f32_16x16x32_bf16 v[46:49], v[180:183], v[214:217], v[46:49]
	v_mfma_f32_16x16x32_bf16 v[42:45], v[188:191], v[214:217], v[42:45]
	s_waitcnt lgkmcnt(0)
	v_mfma_f32_16x16x32_bf16 v[38:41], v[180:183], v[222:225], v[38:41]
	v_mfma_f32_16x16x32_bf16 v[34:37], v[188:191], v[222:225], v[34:37]
	s_barrier
	v_lshl_add_u64 v[170:171], v[170:171], 0, s[18:19]
	s_add_i32 s9, s57, s39
	v_lshl_add_u64 v[176:177], v[170:171], 0, v[134:135]
	s_mov_b32 m0, s9
	v_lshl_add_u64 v[170:171], v[170:171], 0, v[144:145]
	global_load_lds_dwordx4 v[176:177], off
	s_add_i32 m0, s9, 0x2000
	s_nop 0
	global_load_lds_dwordx4 v[170:171], off
	s_waitcnt vmcnt(6)
	s_barrier
	v_mfma_f32_16x16x32_bf16 v[30:33], v[228:231], v[192:195], v[30:33]
	v_mfma_f32_16x16x32_bf16 v[26:29], v[236:239], v[192:195], v[26:29]
	v_mfma_f32_16x16x32_bf16 v[22:25], v[228:231], v[200:203], v[22:25]
	v_mfma_f32_16x16x32_bf16 v[18:21], v[236:239], v[200:203], v[18:21]
	v_mfma_f32_16x16x32_bf16 v[14:17], v[228:231], v[210:213], v[14:17]
	v_mfma_f32_16x16x32_bf16 v[10:13], v[236:239], v[210:213], v[10:13]
	v_mfma_f32_16x16x32_bf16 v[6:9], v[228:231], v[218:221], v[6:9]
	v_mfma_f32_16x16x32_bf16 v[2:5], v[236:239], v[218:221], v[2:5]
	v_mfma_f32_16x16x32_bf16 v[30:33], v[232:235], v[196:199], v[30:33]
	v_mfma_f32_16x16x32_bf16 v[26:29], v[240:243], v[196:199], v[26:29]
	v_mfma_f32_16x16x32_bf16 v[22:25], v[232:235], v[204:207], v[22:25]
	v_mfma_f32_16x16x32_bf16 v[18:21], v[240:243], v[204:207], v[18:21]
	v_mfma_f32_16x16x32_bf16 v[14:17], v[232:235], v[214:217], v[14:17]
	v_mfma_f32_16x16x32_bf16 v[10:13], v[240:243], v[214:217], v[10:13]
	v_mfma_f32_16x16x32_bf16 v[6:9], v[232:235], v[222:225], v[6:9]
	v_mfma_f32_16x16x32_bf16 v[2:5], v[240:243], v[222:225], v[2:5]
	s_add_i32 s8, s8, 2
	s_add_u32 s6, s6, 0x100
	s_addc_u32 s7, s7, 0
	s_cmp_lt_u32 s8, 14
	s_barrier
	s_cbranch_scc1 .LBB0_914
	s_waitcnt vmcnt(0)
	s_cmpk_gt_u32 s38, 0xff
	s_cbranch_scc1 .LBB0_917
	s_barrier

.LBB0_1128:
	s_add_u32 s38, s6, 0xf8cd0080
	s_addc_u32 s39, s7, -1
	s_cmp_lg_u32 s37, 40
	s_cselect_b32 s39, s39, 0
	s_cselect_b32 s38, s38, 0
	s_add_i32 s40, 0, 0x10000
	v_add_u32_e32 v164, s40, v169
	ds_read_b128 v[172:175], v164
	ds_read_b128 v[176:179], v164 offset:1024
	ds_read_b128 v[180:183], v164 offset:2048
	ds_read_b128 v[184:187], v164 offset:3072
	v_lshl_add_u64 v[240:241], v[150:151], 0, s[38:39]
	v_lshl_add_u64 v[164:165], v[148:149], 0, s[38:39]
	v_lshl_add_u64 v[222:223], v[152:153], 0, s[6:7]
	s_add_i32 m0, s28, 0xc000
	ds_read_b128 v[188:191], v170
	ds_read_b128 v[192:195], v170 offset:1024
	ds_read_b128 v[196:199], v170 offset:2048
	ds_read_b128 v[200:203], v170 offset:3072
	ds_read_b128 v[204:207], v170 offset:4096
	ds_read_b128 v[210:213], v170 offset:5120
	ds_read_b128 v[214:217], v170 offset:6144
	ds_read_b128 v[218:221], v170 offset:7168
	global_load_lds_dwordx4 v[222:223], off
	v_lshl_add_u64 v[222:223], v[162:163], 0, s[6:7]
	s_add_i32 m0, s28, 0xe000
	s_nop 0
	global_load_lds_dwordx4 v[222:223], off
	s_waitcnt lgkmcnt(8)
	s_barrier
	s_waitcnt lgkmcnt(7)
	v_mfma_f32_16x16x32_bf16 v[126:129], v[172:175], v[188:191], v[126:129]
	v_mfma_f32_16x16x32_bf16 v[122:125], v[180:183], v[188:191], v[122:125]
	s_waitcnt lgkmcnt(5)
	v_mfma_f32_16x16x32_bf16 v[118:121], v[172:175], v[196:199], v[118:121]
	v_mfma_f32_16x16x32_bf16 v[114:117], v[180:183], v[196:199], v[114:117]
	s_waitcnt lgkmcnt(3)
	v_mfma_f32_16x16x32_bf16 v[110:113], v[172:175], v[204:207], v[110:113]
	v_mfma_f32_16x16x32_bf16 v[106:109], v[180:183], v[204:207], v[106:109]
	s_waitcnt lgkmcnt(1)
	v_mfma_f32_16x16x32_bf16 v[102:105], v[172:175], v[214:217], v[102:105]
	v_mfma_f32_16x16x32_bf16 v[98:101], v[180:183], v[214:217], v[98:101]
	v_mfma_f32_16x16x32_bf16 v[126:129], v[176:179], v[192:195], v[126:129]
	v_mfma_f32_16x16x32_bf16 v[122:125], v[184:187], v[192:195], v[122:125]
	v_mfma_f32_16x16x32_bf16 v[118:121], v[176:179], v[200:203], v[118:121]
	v_mfma_f32_16x16x32_bf16 v[114:117], v[184:187], v[200:203], v[114:117]
	v_mfma_f32_16x16x32_bf16 v[110:113], v[176:179], v[210:213], v[110:113]
	v_mfma_f32_16x16x32_bf16 v[106:109], v[184:187], v[210:213], v[106:109]
	s_waitcnt lgkmcnt(0)
	v_mfma_f32_16x16x32_bf16 v[102:105], v[176:179], v[218:221], v[102:105]
	v_mfma_f32_16x16x32_bf16 v[98:101], v[184:187], v[218:221], v[98:101]
	s_barrier
	s_add_i32 s38, 0, 0x14000
	s_add_i32 s39, s40, s27
	v_add_u32_e32 v171, s38, v169
	v_lshl_add_u64 v[242:243], v[164:165], 0, v[138:139]
	s_mov_b32 m0, s39
	ds_read_b128 v[222:225], v171
	ds_read_b128 v[228:231], v171 offset:1024
	ds_read_b128 v[232:235], v171 offset:2048
	ds_read_b128 v[236:239], v171 offset:3072
	global_load_lds_dwordx4 v[242:243], off
	v_lshl_add_u64 v[244:245], v[164:165], 0, v[146:147]
	s_add_i32 m0, s39, 0x2000
	s_nop 0
	global_load_lds_dwordx4 v[244:245], off
	s_barrier
	s_waitcnt lgkmcnt(3)
	v_mfma_f32_16x16x32_bf16 v[94:97], v[222:225], v[188:191], v[94:97]
	s_waitcnt lgkmcnt(1)
	v_mfma_f32_16x16x32_bf16 v[90:93], v[232:235], v[188:191], v[90:93]
	v_mfma_f32_16x16x32_bf16 v[86:89], v[222:225], v[196:199], v[86:89]
	v_mfma_f32_16x16x32_bf16 v[82:85], v[232:235], v[196:199], v[82:85]
	v_mfma_f32_16x16x32_bf16 v[78:81], v[222:225], v[204:207], v[78:81]
	v_mfma_f32_16x16x32_bf16 v[74:77], v[232:235], v[204:207], v[74:77]
	v_mfma_f32_16x16x32_bf16 v[70:73], v[222:225], v[214:217], v[70:73]
	v_mfma_f32_16x16x32_bf16 v[66:69], v[232:235], v[214:217], v[66:69]
	v_mfma_f32_16x16x32_bf16 v[94:97], v[228:231], v[192:195], v[94:97]
	s_waitcnt lgkmcnt(0)
	v_mfma_f32_16x16x32_bf16 v[90:93], v[236:239], v[192:195], v[90:93]
	v_mfma_f32_16x16x32_bf16 v[86:89], v[228:231], v[200:203], v[86:89]
	v_mfma_f32_16x16x32_bf16 v[82:85], v[236:239], v[200:203], v[82:85]
	v_mfma_f32_16x16x32_bf16 v[78:81], v[228:231], v[210:213], v[78:81]
	v_mfma_f32_16x16x32_bf16 v[74:77], v[236:239], v[210:213], v[74:77]
	v_mfma_f32_16x16x32_bf16 v[70:73], v[228:231], v[218:221], v[70:73]
	v_mfma_f32_16x16x32_bf16 v[66:69], v[236:239], v[218:221], v[66:69]
	s_mov_b32 m0, s28
	v_lshl_add_u64 v[246:247], v[240:241], 0, v[138:139]
	s_barrier
	ds_read_b128 v[188:191], v170 offset:16384
	ds_read_b128 v[192:195], v170 offset:17408
	ds_read_b128 v[196:199], v170 offset:18432
	ds_read_b128 v[200:203], v170 offset:19456
	ds_read_b128 v[204:207], v170 offset:20480
	ds_read_b128 v[210:213], v170 offset:21504
	ds_read_b128 v[214:217], v170 offset:22528
	ds_read_b128 v[218:221], v170 offset:23552
	global_load_lds_dwordx4 v[246:247], off
	v_lshl_add_u64 v[248:249], v[240:241], 0, v[146:147]
	s_mov_b32 m0, s29
	s_nop 0
	global_load_lds_dwordx4 v[248:249], off
	s_barrier
	s_waitcnt lgkmcnt(7)
	v_mfma_f32_16x16x32_bf16 v[62:65], v[172:175], v[188:191], v[62:65]
	v_mfma_f32_16x16x32_bf16 v[58:61], v[180:183], v[188:191], v[58:61]
	s_waitcnt lgkmcnt(5)
	v_mfma_f32_16x16x32_bf16 v[54:57], v[172:175], v[196:199], v[54:57]
	v_mfma_f32_16x16x32_bf16 v[50:53], v[180:183], v[196:199], v[50:53]
	s_waitcnt lgkmcnt(3)
	v_mfma_f32_16x16x32_bf16 v[46:49], v[172:175], v[204:207], v[46:49]
	v_mfma_f32_16x16x32_bf16 v[42:45], v[180:183], v[204:207], v[42:45]
	s_waitcnt lgkmcnt(1)
	v_mfma_f32_16x16x32_bf16 v[38:41], v[172:175], v[214:217], v[38:41]
	v_mfma_f32_16x16x32_bf16 v[34:37], v[180:183], v[214:217], v[34:37]
	v_mfma_f32_16x16x32_bf16 v[62:65], v[176:179], v[192:195], v[62:65]
	v_mfma_f32_16x16x32_bf16 v[58:61], v[184:187], v[192:195], v[58:61]
	v_mfma_f32_16x16x32_bf16 v[54:57], v[176:179], v[200:203], v[54:57]
	v_mfma_f32_16x16x32_bf16 v[50:53], v[184:187], v[200:203], v[50:53]
	v_mfma_f32_16x16x32_bf16 v[46:49], v[176:179], v[210:213], v[46:49]
	v_mfma_f32_16x16x32_bf16 v[42:45], v[184:187], v[210:213], v[42:45]
	s_waitcnt lgkmcnt(0)
	v_mfma_f32_16x16x32_bf16 v[38:41], v[176:179], v[218:221], v[38:41]
	v_mfma_f32_16x16x32_bf16 v[34:37], v[184:187], v[218:221], v[34:37]
	s_barrier
	v_lshl_add_u64 v[172:173], v[164:165], 0, s[16:17]
	s_add_i32 s38, s38, s27
	v_lshl_add_u64 v[174:175], v[172:173], 0, v[138:139]
	s_mov_b32 m0, s38
	v_lshl_add_u64 v[172:173], v[172:173], 0, v[146:147]
	global_load_lds_dwordx4 v[174:175], off
	s_add_i32 m0, s38, 0x2000
	s_nop 0
	global_load_lds_dwordx4 v[172:173], off
	s_waitcnt vmcnt(6)
	s_barrier
	v_mfma_f32_16x16x32_bf16 v[30:33], v[222:225], v[188:191], v[30:33]
	v_mfma_f32_16x16x32_bf16 v[26:29], v[232:235], v[188:191], v[26:29]
	v_mfma_f32_16x16x32_bf16 v[22:25], v[222:225], v[196:199], v[22:25]
	v_mfma_f32_16x16x32_bf16 v[18:21], v[232:235], v[196:199], v[18:21]
	v_mfma_f32_16x16x32_bf16 v[14:17], v[222:225], v[204:207], v[14:17]
	v_mfma_f32_16x16x32_bf16 v[10:13], v[232:235], v[204:207], v[10:13]
	v_mfma_f32_16x16x32_bf16 v[6:9], v[222:225], v[214:217], v[6:9]
	v_mfma_f32_16x16x32_bf16 v[2:5], v[232:235], v[214:217], v[2:5]
	v_mfma_f32_16x16x32_bf16 v[30:33], v[228:231], v[192:195], v[30:33]
	v_mfma_f32_16x16x32_bf16 v[26:29], v[236:239], v[192:195], v[26:29]
	v_mfma_f32_16x16x32_bf16 v[22:25], v[228:231], v[200:203], v[22:25]
	v_mfma_f32_16x16x32_bf16 v[18:21], v[236:239], v[200:203], v[18:21]
	v_mfma_f32_16x16x32_bf16 v[14:17], v[228:231], v[210:213], v[14:17]
	v_mfma_f32_16x16x32_bf16 v[10:13], v[236:239], v[210:213], v[10:13]
	v_mfma_f32_16x16x32_bf16 v[6:9], v[228:231], v[218:221], v[6:9]
	v_mfma_f32_16x16x32_bf16 v[2:5], v[236:239], v[218:221], v[2:5]
	s_add_i32 s38, 0, 0x18000
	v_add_u32_e32 v171, s38, v169
	s_barrier
	ds_read_b128 v[172:175], v171
	ds_read_b128 v[176:179], v171 offset:1024
	ds_read_b128 v[180:183], v171 offset:2048
	ds_read_b128 v[184:187], v171 offset:3072
	v_lshl_add_u64 v[222:223], v[240:241], 0, s[16:17]
	s_mov_b32 m0, s31
	v_lshl_add_u64 v[224:225], v[222:223], 0, v[138:139]
	ds_read_b128 v[188:191], v170 offset:32768
	ds_read_b128 v[192:195], v170 offset:33792
	ds_read_b128 v[196:199], v170 offset:34816
	ds_read_b128 v[200:203], v170 offset:35840
	ds_read_b128 v[204:207], v170 offset:36864
	ds_read_b128 v[210:213], v170 offset:37888
	ds_read_b128 v[214:217], v170 offset:38912
	ds_read_b128 v[218:221], v170 offset:39936
	global_load_lds_dwordx4 v[224:225], off
	v_lshl_add_u64 v[222:223], v[222:223], 0, v[146:147]
	s_mov_b32 m0, s34
	s_nop 0
	global_load_lds_dwordx4 v[222:223], off
	s_waitcnt lgkmcnt(8)
	s_barrier
	s_waitcnt lgkmcnt(7)
	v_mfma_f32_16x16x32_bf16 v[126:129], v[172:175], v[188:191], v[126:129]
	v_mfma_f32_16x16x32_bf16 v[122:125], v[180:183], v[188:191], v[122:125]
	s_waitcnt lgkmcnt(5)
	v_mfma_f32_16x16x32_bf16 v[118:121], v[172:175], v[196:199], v[118:121]
	v_mfma_f32_16x16x32_bf16 v[114:117], v[180:183], v[196:199], v[114:117]
	s_waitcnt lgkmcnt(3)
	v_mfma_f32_16x16x32_bf16 v[110:113], v[172:175], v[204:207], v[110:113]
	v_mfma_f32_16x16x32_bf16 v[106:109], v[180:183], v[204:207], v[106:109]
	s_waitcnt lgkmcnt(1)
	v_mfma_f32_16x16x32_bf16 v[102:105], v[172:175], v[214:217], v[102:105]
	v_mfma_f32_16x16x32_bf16 v[98:101], v[180:183], v[214:217], v[98:101]
	v_mfma_f32_16x16x32_bf16 v[126:129], v[176:179], v[192:195], v[126:129]
	v_mfma_f32_16x16x32_bf16 v[122:125], v[184:187], v[192:195], v[122:125]
	v_mfma_f32_16x16x32_bf16 v[118:121], v[176:179], v[200:203], v[118:121]
	v_mfma_f32_16x16x32_bf16 v[114:117], v[184:187], v[200:203], v[114:117]
	v_mfma_f32_16x16x32_bf16 v[110:113], v[176:179], v[210:213], v[110:113]
	v_mfma_f32_16x16x32_bf16 v[106:109], v[184:187], v[210:213], v[106:109]
	s_waitcnt lgkmcnt(0)
	v_mfma_f32_16x16x32_bf16 v[102:105], v[176:179], v[218:221], v[102:105]
	v_mfma_f32_16x16x32_bf16 v[98:101], v[184:187], v[218:221], v[98:101]
	s_barrier
	s_add_i32 s39, 0, 0x1c000
	s_add_i32 s38, s38, s27
	v_add_u32_e32 v171, s39, v169
	v_lshl_add_u64 v[240:241], v[242:243], 0, s[18:19]
	s_mov_b32 m0, s38
	ds_read_b128 v[222:225], v171
	ds_read_b128 v[228:231], v171 offset:1024
	ds_read_b128 v[232:235], v171 offset:2048
	ds_read_b128 v[236:239], v171 offset:3072
	global_load_lds_dwordx4 v[240:241], off
	v_lshl_add_u64 v[240:241], v[244:245], 0, s[18:19]
	s_add_i32 m0, s38, 0x2000
	s_nop 0
	global_load_lds_dwordx4 v[240:241], off
	s_barrier
	s_waitcnt lgkmcnt(3)
	v_mfma_f32_16x16x32_bf16 v[94:97], v[222:225], v[188:191], v[94:97]
	s_waitcnt lgkmcnt(1)
	v_mfma_f32_16x16x32_bf16 v[90:93], v[232:235], v[188:191], v[90:93]
	v_mfma_f32_16x16x32_bf16 v[86:89], v[222:225], v[196:199], v[86:89]
	v_mfma_f32_16x16x32_bf16 v[82:85], v[232:235], v[196:199], v[82:85]
	v_mfma_f32_16x16x32_bf16 v[78:81], v[222:225], v[204:207], v[78:81]
	v_mfma_f32_16x16x32_bf16 v[74:77], v[232:235], v[204:207], v[74:77]
	v_mfma_f32_16x16x32_bf16 v[70:73], v[222:225], v[214:217], v[70:73]
	v_mfma_f32_16x16x32_bf16 v[66:69], v[232:235], v[214:217], v[66:69]
	v_mfma_f32_16x16x32_bf16 v[94:97], v[228:231], v[192:195], v[94:97]
	s_waitcnt lgkmcnt(0)
	v_mfma_f32_16x16x32_bf16 v[90:93], v[236:239], v[192:195], v[90:93]
	v_mfma_f32_16x16x32_bf16 v[86:89], v[228:231], v[200:203], v[86:89]
	v_mfma_f32_16x16x32_bf16 v[82:85], v[236:239], v[200:203], v[82:85]
	v_mfma_f32_16x16x32_bf16 v[78:81], v[228:231], v[210:213], v[78:81]
	v_mfma_f32_16x16x32_bf16 v[74:77], v[236:239], v[210:213], v[74:77]
	v_mfma_f32_16x16x32_bf16 v[70:73], v[228:231], v[218:221], v[70:73]
	v_mfma_f32_16x16x32_bf16 v[66:69], v[236:239], v[218:221], v[66:69]
	s_mov_b32 m0, s35
	v_lshl_add_u64 v[240:241], v[246:247], 0, s[18:19]
	s_barrier
	ds_read_b128 v[188:191], v170 offset:49152
	ds_read_b128 v[192:195], v170 offset:50176
	ds_read_b128 v[196:199], v170 offset:51200
	ds_read_b128 v[200:203], v170 offset:52224
	ds_read_b128 v[204:207], v170 offset:53248
	ds_read_b128 v[210:213], v170 offset:54272
	ds_read_b128 v[214:217], v170 offset:55296
	ds_read_b128 v[218:221], v170 offset:56320
	global_load_lds_dwordx4 v[240:241], off
	v_lshl_add_u64 v[240:241], v[248:249], 0, s[18:19]
	s_mov_b32 m0, s36
	s_nop 0
	global_load_lds_dwordx4 v[240:241], off
	s_barrier
	s_waitcnt lgkmcnt(7)
	v_mfma_f32_16x16x32_bf16 v[62:65], v[172:175], v[188:191], v[62:65]
	v_mfma_f32_16x16x32_bf16 v[58:61], v[180:183], v[188:191], v[58:61]
	s_waitcnt lgkmcnt(5)
	v_mfma_f32_16x16x32_bf16 v[54:57], v[172:175], v[196:199], v[54:57]
	v_mfma_f32_16x16x32_bf16 v[50:53], v[180:183], v[196:199], v[50:53]
	s_waitcnt lgkmcnt(3)
	v_mfma_f32_16x16x32_bf16 v[46:49], v[172:175], v[204:207], v[46:49]
	v_mfma_f32_16x16x32_bf16 v[42:45], v[180:183], v[204:207], v[42:45]
	s_waitcnt lgkmcnt(1)
	v_mfma_f32_16x16x32_bf16 v[38:41], v[172:175], v[214:217], v[38:41]
	v_mfma_f32_16x16x32_bf16 v[34:37], v[180:183], v[214:217], v[34:37]
	v_mfma_f32_16x16x32_bf16 v[62:65], v[176:179], v[192:195], v[62:65]
	v_mfma_f32_16x16x32_bf16 v[58:61], v[184:187], v[192:195], v[58:61]
	v_mfma_f32_16x16x32_bf16 v[54:57], v[176:179], v[200:203], v[54:57]
	v_mfma_f32_16x16x32_bf16 v[50:53], v[184:187], v[200:203], v[50:53]
	v_mfma_f32_16x16x32_bf16 v[46:49], v[176:179], v[210:213], v[46:49]
	v_mfma_f32_16x16x32_bf16 v[42:45], v[184:187], v[210:213], v[42:45]
	s_waitcnt lgkmcnt(0)
	v_mfma_f32_16x16x32_bf16 v[38:41], v[176:179], v[218:221], v[38:41]
	v_mfma_f32_16x16x32_bf16 v[34:37], v[184:187], v[218:221], v[34:37]
	s_barrier
	v_lshl_add_u64 v[164:165], v[164:165], 0, s[20:21]
	s_add_i32 s38, s39, s27
	v_lshl_add_u64 v[172:173], v[164:165], 0, v[138:139]
	s_mov_b32 m0, s38
	v_lshl_add_u64 v[164:165], v[164:165], 0, v[146:147]
	global_load_lds_dwordx4 v[172:173], off
	s_add_i32 m0, s38, 0x2000
	s_nop 0
	global_load_lds_dwordx4 v[164:165], off
	s_waitcnt vmcnt(6)
	s_barrier
	v_mfma_f32_16x16x32_bf16 v[30:33], v[222:225], v[188:191], v[30:33]
	v_mfma_f32_16x16x32_bf16 v[26:29], v[232:235], v[188:191], v[26:29]
	v_mfma_f32_16x16x32_bf16 v[22:25], v[222:225], v[196:199], v[22:25]
	v_mfma_f32_16x16x32_bf16 v[18:21], v[232:235], v[196:199], v[18:21]
	v_mfma_f32_16x16x32_bf16 v[14:17], v[222:225], v[204:207], v[14:17]
	v_mfma_f32_16x16x32_bf16 v[10:13], v[232:235], v[204:207], v[10:13]
	v_mfma_f32_16x16x32_bf16 v[6:9], v[222:225], v[214:217], v[6:9]
	v_mfma_f32_16x16x32_bf16 v[2:5], v[232:235], v[214:217], v[2:5]
	v_mfma_f32_16x16x32_bf16 v[30:33], v[228:231], v[192:195], v[30:33]
	v_mfma_f32_16x16x32_bf16 v[26:29], v[236:239], v[192:195], v[26:29]
	v_mfma_f32_16x16x32_bf16 v[22:25], v[228:231], v[200:203], v[22:25]
	v_mfma_f32_16x16x32_bf16 v[18:21], v[236:239], v[200:203], v[18:21]
	v_mfma_f32_16x16x32_bf16 v[14:17], v[228:231], v[210:213], v[14:17]
	v_mfma_f32_16x16x32_bf16 v[10:13], v[236:239], v[210:213], v[10:13]
	v_mfma_f32_16x16x32_bf16 v[6:9], v[228:231], v[218:221], v[6:9]
	v_mfma_f32_16x16x32_bf16 v[2:5], v[236:239], v[218:221], v[2:5]
	s_add_i32 s37, s37, 2
	s_add_u32 s6, s6, 0x100
	s_addc_u32 s7, s7, 0
	s_cmp_lt_u32 s37, 42
	s_barrier
	s_cbranch_scc1 .LBB0_1128
	s_waitcnt vmcnt(0)
	s_cmpk_gt_u32 s26, 0xff
	s_cbranch_scc1 .LBB0_1131
	s_barrier

.LBB0_1271:
	s_cmpk_eq_i32 s6, 0x700
	v_lshl_add_u64 v[170:171], v[162:163], 0, s[6:7]
	v_lshl_add_u64 v[170:171], v[170:171], 0, s[18:19]
	s_cselect_b64 vcc, -1, 0
	s_add_i32 s25, 0, 0x10000
	v_cndmask_b32_e32 v245, v171, v153, vcc
	v_add_u32_e32 v171, s25, v173
	ds_read_b128 v[176:179], v171
	ds_read_b128 v[180:183], v171 offset:1024
	ds_read_b128 v[184:187], v171 offset:2048
	ds_read_b128 v[188:191], v171 offset:3072
	v_cndmask_b32_e32 v244, v170, v152, vcc
	v_lshl_add_u64 v[170:171], v[168:169], 0, s[6:7]
	v_cndmask_b32_e32 v171, v171, v151, vcc
	v_cndmask_b32_e32 v170, v170, v150, vcc
	v_lshl_add_u64 v[228:229], v[164:165], 0, s[6:7]
	s_add_i32 m0, s20, 0xc000
	ds_read_b128 v[192:195], v174
	ds_read_b128 v[196:199], v174 offset:1024
	ds_read_b128 v[200:203], v174 offset:2048
	ds_read_b128 v[204:207], v174 offset:3072
	ds_read_b128 v[210:213], v174 offset:4096
	ds_read_b128 v[214:217], v174 offset:5120
	ds_read_b128 v[218:221], v174 offset:6144
	ds_read_b128 v[222:225], v174 offset:7168
	global_load_lds_dwordx4 v[228:229], off
	v_lshl_add_u64 v[228:229], v[166:167], 0, s[6:7]
	s_add_i32 m0, s20, 0xe000
	s_nop 0
	global_load_lds_dwordx4 v[228:229], off
	s_waitcnt lgkmcnt(8)
	s_barrier
	s_waitcnt lgkmcnt(7)
	v_mfma_f32_16x16x32_bf16 v[126:129], v[176:179], v[192:195], v[126:129]
	v_mfma_f32_16x16x32_bf16 v[122:125], v[184:187], v[192:195], v[122:125]
	s_waitcnt lgkmcnt(5)
	v_mfma_f32_16x16x32_bf16 v[118:121], v[176:179], v[200:203], v[118:121]
	v_mfma_f32_16x16x32_bf16 v[114:117], v[184:187], v[200:203], v[114:117]
	s_waitcnt lgkmcnt(3)
	v_mfma_f32_16x16x32_bf16 v[110:113], v[176:179], v[210:213], v[110:113]
	v_mfma_f32_16x16x32_bf16 v[106:109], v[184:187], v[210:213], v[106:109]
	s_waitcnt lgkmcnt(1)
	v_mfma_f32_16x16x32_bf16 v[102:105], v[176:179], v[218:221], v[102:105]
	v_mfma_f32_16x16x32_bf16 v[98:101], v[184:187], v[218:221], v[98:101]
	v_mfma_f32_16x16x32_bf16 v[126:129], v[180:183], v[196:199], v[126:129]
	v_mfma_f32_16x16x32_bf16 v[122:125], v[188:191], v[196:199], v[122:125]
	v_mfma_f32_16x16x32_bf16 v[118:121], v[180:183], v[204:207], v[118:121]
	v_mfma_f32_16x16x32_bf16 v[114:117], v[188:191], v[204:207], v[114:117]
	v_mfma_f32_16x16x32_bf16 v[110:113], v[180:183], v[214:217], v[110:113]
	v_mfma_f32_16x16x32_bf16 v[106:109], v[188:191], v[214:217], v[106:109]
	s_waitcnt lgkmcnt(0)
	v_mfma_f32_16x16x32_bf16 v[102:105], v[180:183], v[222:225], v[102:105]
	v_mfma_f32_16x16x32_bf16 v[98:101], v[188:191], v[222:225], v[98:101]
	s_barrier
	s_add_i32 s41, 0, 0x14000
	s_add_i32 s25, s25, s35
	v_add_u32_e32 v175, s41, v173
	v_lshl_add_u64 v[246:247], v[170:171], 0, v[138:139]
	s_mov_b32 m0, s25
	ds_read_b128 v[228:231], v175
	ds_read_b128 v[232:235], v175 offset:1024
	ds_read_b128 v[236:239], v175 offset:2048
	ds_read_b128 v[240:243], v175 offset:3072
	global_load_lds_dwordx4 v[246:247], off
	v_lshl_add_u64 v[248:249], v[170:171], 0, v[148:149]
	s_add_i32 m0, s25, 0x2000
	s_nop 0
	global_load_lds_dwordx4 v[248:249], off
	s_barrier
	s_waitcnt lgkmcnt(3)
	v_mfma_f32_16x16x32_bf16 v[94:97], v[228:231], v[192:195], v[94:97]
	s_waitcnt lgkmcnt(1)
	v_mfma_f32_16x16x32_bf16 v[90:93], v[236:239], v[192:195], v[90:93]
	v_mfma_f32_16x16x32_bf16 v[86:89], v[228:231], v[200:203], v[86:89]
	v_mfma_f32_16x16x32_bf16 v[82:85], v[236:239], v[200:203], v[82:85]
	v_mfma_f32_16x16x32_bf16 v[78:81], v[228:231], v[210:213], v[78:81]
	v_mfma_f32_16x16x32_bf16 v[74:77], v[236:239], v[210:213], v[74:77]
	v_mfma_f32_16x16x32_bf16 v[70:73], v[228:231], v[218:221], v[70:73]
	v_mfma_f32_16x16x32_bf16 v[66:69], v[236:239], v[218:221], v[66:69]
	v_mfma_f32_16x16x32_bf16 v[94:97], v[232:235], v[196:199], v[94:97]
	s_waitcnt lgkmcnt(0)
	v_mfma_f32_16x16x32_bf16 v[90:93], v[240:243], v[196:199], v[90:93]
	v_mfma_f32_16x16x32_bf16 v[86:89], v[232:235], v[204:207], v[86:89]
	v_mfma_f32_16x16x32_bf16 v[82:85], v[240:243], v[204:207], v[82:85]
	v_mfma_f32_16x16x32_bf16 v[78:81], v[232:235], v[214:217], v[78:81]
	v_mfma_f32_16x16x32_bf16 v[74:77], v[240:243], v[214:217], v[74:77]
	v_mfma_f32_16x16x32_bf16 v[70:73], v[232:235], v[222:225], v[70:73]
	v_mfma_f32_16x16x32_bf16 v[66:69], v[240:243], v[222:225], v[66:69]
	s_mov_b32 m0, s20
	v_lshl_add_u64 v[250:251], v[244:245], 0, v[138:139]
	s_barrier
	ds_read_b128 v[192:195], v174 offset:16384
	ds_read_b128 v[196:199], v174 offset:17408
	ds_read_b128 v[200:203], v174 offset:18432
	ds_read_b128 v[204:207], v174 offset:19456
	ds_read_b128 v[210:213], v174 offset:20480
	ds_read_b128 v[214:217], v174 offset:21504
	ds_read_b128 v[218:221], v174 offset:22528
	ds_read_b128 v[222:225], v174 offset:23552
	global_load_lds_dwordx4 v[250:251], off
	v_lshl_add_u64 v[252:253], v[244:245], 0, v[148:149]
	s_mov_b32 m0, s36
	s_nop 0
	global_load_lds_dwordx4 v[252:253], off
	s_barrier
	s_waitcnt lgkmcnt(7)
	v_mfma_f32_16x16x32_bf16 v[62:65], v[176:179], v[192:195], v[62:65]
	v_mfma_f32_16x16x32_bf16 v[58:61], v[184:187], v[192:195], v[58:61]
	s_waitcnt lgkmcnt(5)
	v_mfma_f32_16x16x32_bf16 v[54:57], v[176:179], v[200:203], v[54:57]
	v_mfma_f32_16x16x32_bf16 v[50:53], v[184:187], v[200:203], v[50:53]
	s_waitcnt lgkmcnt(3)
	v_mfma_f32_16x16x32_bf16 v[46:49], v[176:179], v[210:213], v[46:49]
	v_mfma_f32_16x16x32_bf16 v[42:45], v[184:187], v[210:213], v[42:45]
	s_waitcnt lgkmcnt(1)
	v_mfma_f32_16x16x32_bf16 v[38:41], v[176:179], v[218:221], v[38:41]
	v_mfma_f32_16x16x32_bf16 v[34:37], v[184:187], v[218:221], v[34:37]
	v_mfma_f32_16x16x32_bf16 v[62:65], v[180:183], v[196:199], v[62:65]
	v_mfma_f32_16x16x32_bf16 v[58:61], v[188:191], v[196:199], v[58:61]
	v_mfma_f32_16x16x32_bf16 v[54:57], v[180:183], v[204:207], v[54:57]
	v_mfma_f32_16x16x32_bf16 v[50:53], v[188:191], v[204:207], v[50:53]
	v_mfma_f32_16x16x32_bf16 v[46:49], v[180:183], v[214:217], v[46:49]
	v_mfma_f32_16x16x32_bf16 v[42:45], v[188:191], v[214:217], v[42:45]
	s_waitcnt lgkmcnt(0)
	v_mfma_f32_16x16x32_bf16 v[38:41], v[180:183], v[222:225], v[38:41]
	v_mfma_f32_16x16x32_bf16 v[34:37], v[188:191], v[222:225], v[34:37]
	s_barrier
	v_lshl_add_u64 v[176:177], v[170:171], 0, s[12:13]
	s_add_i32 s25, s41, s35
	v_lshl_add_u64 v[178:179], v[176:177], 0, v[138:139]
	s_mov_b32 m0, s25
	v_lshl_add_u64 v[176:177], v[176:177], 0, v[148:149]
	global_load_lds_dwordx4 v[178:179], off
	s_add_i32 m0, s25, 0x2000
	s_nop 0
	global_load_lds_dwordx4 v[176:177], off
	s_waitcnt vmcnt(6)
	s_barrier
	v_mfma_f32_16x16x32_bf16 v[30:33], v[228:231], v[192:195], v[30:33]
	v_mfma_f32_16x16x32_bf16 v[26:29], v[236:239], v[192:195], v[26:29]
	v_mfma_f32_16x16x32_bf16 v[22:25], v[228:231], v[200:203], v[22:25]
	v_mfma_f32_16x16x32_bf16 v[18:21], v[236:239], v[200:203], v[18:21]
	v_mfma_f32_16x16x32_bf16 v[14:17], v[228:231], v[210:213], v[14:17]
	v_mfma_f32_16x16x32_bf16 v[10:13], v[236:239], v[210:213], v[10:13]
	v_mfma_f32_16x16x32_bf16 v[6:9], v[228:231], v[218:221], v[6:9]
	v_mfma_f32_16x16x32_bf16 v[2:5], v[236:239], v[218:221], v[2:5]
	v_mfma_f32_16x16x32_bf16 v[30:33], v[232:235], v[196:199], v[30:33]
	v_mfma_f32_16x16x32_bf16 v[26:29], v[240:243], v[196:199], v[26:29]
	v_mfma_f32_16x16x32_bf16 v[22:25], v[232:235], v[204:207], v[22:25]
	v_mfma_f32_16x16x32_bf16 v[18:21], v[240:243], v[204:207], v[18:21]
	v_mfma_f32_16x16x32_bf16 v[14:17], v[232:235], v[214:217], v[14:17]
	v_mfma_f32_16x16x32_bf16 v[10:13], v[240:243], v[214:217], v[10:13]
	v_mfma_f32_16x16x32_bf16 v[6:9], v[232:235], v[222:225], v[6:9]
	v_mfma_f32_16x16x32_bf16 v[2:5], v[240:243], v[222:225], v[2:5]
	s_add_i32 s25, 0, 0x18000
	v_add_u32_e32 v175, s25, v173
	s_barrier
	ds_read_b128 v[176:179], v175
	ds_read_b128 v[180:183], v175 offset:1024
	ds_read_b128 v[184:187], v175 offset:2048
	ds_read_b128 v[188:191], v175 offset:3072
	v_lshl_add_u64 v[228:229], v[244:245], 0, s[12:13]
	s_mov_b32 m0, s37
	v_lshl_add_u64 v[230:231], v[228:229], 0, v[138:139]
	ds_read_b128 v[192:195], v174 offset:32768
	ds_read_b128 v[196:199], v174 offset:33792
	ds_read_b128 v[200:203], v174 offset:34816
	ds_read_b128 v[204:207], v174 offset:35840
	ds_read_b128 v[210:213], v174 offset:36864
	ds_read_b128 v[214:217], v174 offset:37888
	ds_read_b128 v[218:221], v174 offset:38912
	ds_read_b128 v[222:225], v174 offset:39936
	global_load_lds_dwordx4 v[230:231], off
	v_lshl_add_u64 v[228:229], v[228:229], 0, v[148:149]
	s_mov_b32 m0, s38
	s_nop 0
	global_load_lds_dwordx4 v[228:229], off
	s_waitcnt lgkmcnt(8)
	s_barrier
	s_waitcnt lgkmcnt(7)
	v_mfma_f32_16x16x32_bf16 v[126:129], v[176:179], v[192:195], v[126:129]
	v_mfma_f32_16x16x32_bf16 v[122:125], v[184:187], v[192:195], v[122:125]
	s_waitcnt lgkmcnt(5)
	v_mfma_f32_16x16x32_bf16 v[118:121], v[176:179], v[200:203], v[118:121]
	v_mfma_f32_16x16x32_bf16 v[114:117], v[184:187], v[200:203], v[114:117]
	s_waitcnt lgkmcnt(3)
	v_mfma_f32_16x16x32_bf16 v[110:113], v[176:179], v[210:213], v[110:113]
	v_mfma_f32_16x16x32_bf16 v[106:109], v[184:187], v[210:213], v[106:109]
	s_waitcnt lgkmcnt(1)
	v_mfma_f32_16x16x32_bf16 v[102:105], v[176:179], v[218:221], v[102:105]
	v_mfma_f32_16x16x32_bf16 v[98:101], v[184:187], v[218:221], v[98:101]
	v_mfma_f32_16x16x32_bf16 v[126:129], v[180:183], v[196:199], v[126:129]
	v_mfma_f32_16x16x32_bf16 v[122:125], v[188:191], v[196:199], v[122:125]
	v_mfma_f32_16x16x32_bf16 v[118:121], v[180:183], v[204:207], v[118:121]
	v_mfma_f32_16x16x32_bf16 v[114:117], v[188:191], v[204:207], v[114:117]
	v_mfma_f32_16x16x32_bf16 v[110:113], v[180:183], v[214:217], v[110:113]
	v_mfma_f32_16x16x32_bf16 v[106:109], v[188:191], v[214:217], v[106:109]
	s_waitcnt lgkmcnt(0)
	v_mfma_f32_16x16x32_bf16 v[102:105], v[180:183], v[222:225], v[102:105]
	v_mfma_f32_16x16x32_bf16 v[98:101], v[188:191], v[222:225], v[98:101]
	s_barrier
	s_add_i32 s41, 0, 0x1c000
	s_add_i32 s25, s25, s35
	v_add_u32_e32 v175, s41, v173
	v_lshl_add_u64 v[244:245], v[246:247], 0, s[14:15]
	s_mov_b32 m0, s25
	ds_read_b128 v[228:231], v175
	ds_read_b128 v[232:235], v175 offset:1024
	ds_read_b128 v[236:239], v175 offset:2048
	ds_read_b128 v[240:243], v175 offset:3072
	global_load_lds_dwordx4 v[244:245], off
	v_lshl_add_u64 v[244:245], v[248:249], 0, s[14:15]
	s_add_i32 m0, s25, 0x2000
	s_nop 0
	global_load_lds_dwordx4 v[244:245], off
	s_barrier
	s_waitcnt lgkmcnt(3)
	v_mfma_f32_16x16x32_bf16 v[94:97], v[228:231], v[192:195], v[94:97]
	s_waitcnt lgkmcnt(1)
	v_mfma_f32_16x16x32_bf16 v[90:93], v[236:239], v[192:195], v[90:93]
	v_mfma_f32_16x16x32_bf16 v[86:89], v[228:231], v[200:203], v[86:89]
	v_mfma_f32_16x16x32_bf16 v[82:85], v[236:239], v[200:203], v[82:85]
	v_mfma_f32_16x16x32_bf16 v[78:81], v[228:231], v[210:213], v[78:81]
	v_mfma_f32_16x16x32_bf16 v[74:77], v[236:239], v[210:213], v[74:77]
	v_mfma_f32_16x16x32_bf16 v[70:73], v[228:231], v[218:221], v[70:73]
	v_mfma_f32_16x16x32_bf16 v[66:69], v[236:239], v[218:221], v[66:69]
	v_mfma_f32_16x16x32_bf16 v[94:97], v[232:235], v[196:199], v[94:97]
	s_waitcnt lgkmcnt(0)
	v_mfma_f32_16x16x32_bf16 v[90:93], v[240:243], v[196:199], v[90:93]
	v_mfma_f32_16x16x32_bf16 v[86:89], v[232:235], v[204:207], v[86:89]
	v_mfma_f32_16x16x32_bf16 v[82:85], v[240:243], v[204:207], v[82:85]
	v_mfma_f32_16x16x32_bf16 v[78:81], v[232:235], v[214:217], v[78:81]
	v_mfma_f32_16x16x32_bf16 v[74:77], v[240:243], v[214:217], v[74:77]
	v_mfma_f32_16x16x32_bf16 v[70:73], v[232:235], v[222:225], v[70:73]
	v_mfma_f32_16x16x32_bf16 v[66:69], v[240:243], v[222:225], v[66:69]
	s_mov_b32 m0, s39
	v_lshl_add_u64 v[244:245], v[250:251], 0, s[14:15]
	s_barrier
	ds_read_b128 v[192:195], v174 offset:49152
	ds_read_b128 v[196:199], v174 offset:50176
	ds_read_b128 v[200:203], v174 offset:51200
	ds_read_b128 v[204:207], v174 offset:52224
	ds_read_b128 v[210:213], v174 offset:53248
	ds_read_b128 v[214:217], v174 offset:54272
	ds_read_b128 v[218:221], v174 offset:55296
	ds_read_b128 v[222:225], v174 offset:56320
	global_load_lds_dwordx4 v[244:245], off
	v_lshl_add_u64 v[244:245], v[252:253], 0, s[14:15]
	s_mov_b32 m0, s40
	s_nop 0
	global_load_lds_dwordx4 v[244:245], off
	s_barrier
	s_waitcnt lgkmcnt(7)
	v_mfma_f32_16x16x32_bf16 v[62:65], v[176:179], v[192:195], v[62:65]
	v_mfma_f32_16x16x32_bf16 v[58:61], v[184:187], v[192:195], v[58:61]
	s_waitcnt lgkmcnt(5)
	v_mfma_f32_16x16x32_bf16 v[54:57], v[176:179], v[200:203], v[54:57]
	v_mfma_f32_16x16x32_bf16 v[50:53], v[184:187], v[200:203], v[50:53]
	s_waitcnt lgkmcnt(3)
	v_mfma_f32_16x16x32_bf16 v[46:49], v[176:179], v[210:213], v[46:49]
	v_mfma_f32_16x16x32_bf16 v[42:45], v[184:187], v[210:213], v[42:45]
	s_waitcnt lgkmcnt(1)
	v_mfma_f32_16x16x32_bf16 v[38:41], v[176:179], v[218:221], v[38:41]
	v_mfma_f32_16x16x32_bf16 v[34:37], v[184:187], v[218:221], v[34:37]
	v_mfma_f32_16x16x32_bf16 v[62:65], v[180:183], v[196:199], v[62:65]
	v_mfma_f32_16x16x32_bf16 v[58:61], v[188:191], v[196:199], v[58:61]
	v_mfma_f32_16x16x32_bf16 v[54:57], v[180:183], v[204:207], v[54:57]
	v_mfma_f32_16x16x32_bf16 v[50:53], v[188:191], v[204:207], v[50:53]
	v_mfma_f32_16x16x32_bf16 v[46:49], v[180:183], v[214:217], v[46:49]
	v_mfma_f32_16x16x32_bf16 v[42:45], v[188:191], v[214:217], v[42:45]
	s_waitcnt lgkmcnt(0)
	v_mfma_f32_16x16x32_bf16 v[38:41], v[180:183], v[222:225], v[38:41]
	v_mfma_f32_16x16x32_bf16 v[34:37], v[188:191], v[222:225], v[34:37]
	s_barrier
	v_lshl_add_u64 v[170:171], v[170:171], 0, s[16:17]
	s_add_i32 s25, s41, s35
	v_lshl_add_u64 v[176:177], v[170:171], 0, v[138:139]
	s_mov_b32 m0, s25
	v_lshl_add_u64 v[170:171], v[170:171], 0, v[148:149]
	global_load_lds_dwordx4 v[176:177], off
	s_add_i32 m0, s25, 0x2000
	s_nop 0
	global_load_lds_dwordx4 v[170:171], off
	s_waitcnt vmcnt(6)
	s_barrier
	v_mfma_f32_16x16x32_bf16 v[30:33], v[228:231], v[192:195], v[30:33]
	v_mfma_f32_16x16x32_bf16 v[26:29], v[236:239], v[192:195], v[26:29]
	v_mfma_f32_16x16x32_bf16 v[22:25], v[228:231], v[200:203], v[22:25]
	v_mfma_f32_16x16x32_bf16 v[18:21], v[236:239], v[200:203], v[18:21]
	v_mfma_f32_16x16x32_bf16 v[14:17], v[228:231], v[210:213], v[14:17]
	v_mfma_f32_16x16x32_bf16 v[10:13], v[236:239], v[210:213], v[10:13]
	v_mfma_f32_16x16x32_bf16 v[6:9], v[228:231], v[218:221], v[6:9]
	v_mfma_f32_16x16x32_bf16 v[2:5], v[236:239], v[218:221], v[2:5]
	v_mfma_f32_16x16x32_bf16 v[30:33], v[232:235], v[196:199], v[30:33]
	v_mfma_f32_16x16x32_bf16 v[26:29], v[240:243], v[196:199], v[26:29]
	v_mfma_f32_16x16x32_bf16 v[22:25], v[232:235], v[204:207], v[22:25]
	v_mfma_f32_16x16x32_bf16 v[18:21], v[240:243], v[204:207], v[18:21]
	v_mfma_f32_16x16x32_bf16 v[14:17], v[232:235], v[214:217], v[14:17]
	v_mfma_f32_16x16x32_bf16 v[10:13], v[240:243], v[214:217], v[10:13]
	v_mfma_f32_16x16x32_bf16 v[6:9], v[232:235], v[222:225], v[6:9]
	v_mfma_f32_16x16x32_bf16 v[2:5], v[240:243], v[222:225], v[2:5]
	s_add_i32 s24, s24, 2
	s_add_u32 s6, s6, 0x100
	s_addc_u32 s7, s7, 0
	s_cmp_lt_u32 s24, 14
	s_barrier
	s_cbranch_scc1 .LBB0_1271
	s_waitcnt vmcnt(0)
	s_cmpk_gt_u32 s27, 0xff
	s_cbranch_scc1 .LBB0_1274
	s_barrier

.LBB0_1645:
	s_add_u32 s33, s6, 0xfbd40080
	s_addc_u32 s34, s7, -1
	s_cmp_lg_u32 s31, 12
	s_cselect_b32 s35, s34, 0
	s_cselect_b32 s34, s33, 0
	s_add_i32 s33, 0, 0x10000
	v_add_u32_e32 v164, s33, v167
	ds_read_b128 v[170:173], v164
	ds_read_b128 v[174:177], v164 offset:1024
	ds_read_b128 v[178:181], v164 offset:2048
	ds_read_b128 v[182:185], v164 offset:3072
	v_lshl_add_u64 v[206:207], v[150:151], 0, s[34:35]
	v_lshl_add_u64 v[164:165], v[148:149], 0, s[34:35]
	v_lshl_add_u64 v[222:223], v[152:153], 0, s[6:7]
	s_add_i32 m0, s17, 0xc000
	ds_read_b128 v[186:189], v168
	ds_read_b128 v[190:193], v168 offset:1024
	ds_read_b128 v[194:197], v168 offset:2048
	ds_read_b128 v[198:201], v168 offset:3072
	ds_read_b128 v[202:205], v168 offset:4096
	ds_read_b128 v[210:213], v168 offset:5120
	ds_read_b128 v[214:217], v168 offset:6144
	ds_read_b128 v[218:221], v168 offset:7168
	global_load_lds_dwordx4 v[222:223], off
	v_lshl_add_u64 v[222:223], v[162:163], 0, s[6:7]
	s_add_i32 m0, s17, 0xe000
	s_nop 0
	global_load_lds_dwordx4 v[222:223], off
	s_waitcnt lgkmcnt(8)
	s_barrier
	s_waitcnt lgkmcnt(7)
	v_mfma_f32_16x16x32_bf16 v[126:129], v[170:173], v[186:189], v[126:129]
	v_mfma_f32_16x16x32_bf16 v[122:125], v[178:181], v[186:189], v[122:125]
	s_waitcnt lgkmcnt(5)
	v_mfma_f32_16x16x32_bf16 v[118:121], v[170:173], v[194:197], v[118:121]
	v_mfma_f32_16x16x32_bf16 v[114:117], v[178:181], v[194:197], v[114:117]
	s_waitcnt lgkmcnt(3)
	v_mfma_f32_16x16x32_bf16 v[110:113], v[170:173], v[202:205], v[110:113]
	v_mfma_f32_16x16x32_bf16 v[106:109], v[178:181], v[202:205], v[106:109]
	s_waitcnt lgkmcnt(1)
	v_mfma_f32_16x16x32_bf16 v[102:105], v[170:173], v[214:217], v[102:105]
	v_mfma_f32_16x16x32_bf16 v[98:101], v[178:181], v[214:217], v[98:101]
	v_mfma_f32_16x16x32_bf16 v[126:129], v[174:177], v[190:193], v[126:129]
	v_mfma_f32_16x16x32_bf16 v[122:125], v[182:185], v[190:193], v[122:125]
	v_mfma_f32_16x16x32_bf16 v[118:121], v[174:177], v[198:201], v[118:121]
	v_mfma_f32_16x16x32_bf16 v[114:117], v[182:185], v[198:201], v[114:117]
	v_mfma_f32_16x16x32_bf16 v[110:113], v[174:177], v[210:213], v[110:113]
	v_mfma_f32_16x16x32_bf16 v[106:109], v[182:185], v[210:213], v[106:109]
	s_waitcnt lgkmcnt(0)
	v_mfma_f32_16x16x32_bf16 v[102:105], v[174:177], v[218:221], v[102:105]
	v_mfma_f32_16x16x32_bf16 v[98:101], v[182:185], v[218:221], v[98:101]
	s_barrier
	s_add_i32 s34, 0, 0x14000
	s_add_i32 s33, s33, s25
	v_add_u32_e32 v169, s34, v167
	v_lshl_add_u64 v[240:241], v[164:165], 0, v[138:139]
	s_mov_b32 m0, s33
	ds_read_b128 v[222:225], v169
	ds_read_b128 v[228:231], v169 offset:1024
	ds_read_b128 v[232:235], v169 offset:2048
	ds_read_b128 v[236:239], v169 offset:3072
	global_load_lds_dwordx4 v[240:241], off
	v_lshl_add_u64 v[242:243], v[164:165], 0, v[146:147]
	s_add_i32 m0, s33, 0x2000
	s_nop 0
	global_load_lds_dwordx4 v[242:243], off
	s_barrier
	s_waitcnt lgkmcnt(3)
	v_mfma_f32_16x16x32_bf16 v[94:97], v[222:225], v[186:189], v[94:97]
	s_waitcnt lgkmcnt(1)
	v_mfma_f32_16x16x32_bf16 v[90:93], v[232:235], v[186:189], v[90:93]
	v_mfma_f32_16x16x32_bf16 v[86:89], v[222:225], v[194:197], v[86:89]
	v_mfma_f32_16x16x32_bf16 v[82:85], v[232:235], v[194:197], v[82:85]
	v_mfma_f32_16x16x32_bf16 v[78:81], v[222:225], v[202:205], v[78:81]
	v_mfma_f32_16x16x32_bf16 v[74:77], v[232:235], v[202:205], v[74:77]
	v_mfma_f32_16x16x32_bf16 v[70:73], v[222:225], v[214:217], v[70:73]
	v_mfma_f32_16x16x32_bf16 v[66:69], v[232:235], v[214:217], v[66:69]
	v_mfma_f32_16x16x32_bf16 v[94:97], v[228:231], v[190:193], v[94:97]
	s_waitcnt lgkmcnt(0)
	v_mfma_f32_16x16x32_bf16 v[90:93], v[236:239], v[190:193], v[90:93]
	v_mfma_f32_16x16x32_bf16 v[86:89], v[228:231], v[198:201], v[86:89]
	v_mfma_f32_16x16x32_bf16 v[82:85], v[236:239], v[198:201], v[82:85]
	v_mfma_f32_16x16x32_bf16 v[78:81], v[228:231], v[210:213], v[78:81]
	v_mfma_f32_16x16x32_bf16 v[74:77], v[236:239], v[210:213], v[74:77]
	v_mfma_f32_16x16x32_bf16 v[70:73], v[228:231], v[218:221], v[70:73]
	v_mfma_f32_16x16x32_bf16 v[66:69], v[236:239], v[218:221], v[66:69]
	s_mov_b32 m0, s17
	v_lshl_add_u64 v[244:245], v[206:207], 0, v[138:139]
	s_barrier
	ds_read_b128 v[186:189], v168 offset:16384
	ds_read_b128 v[190:193], v168 offset:17408
	ds_read_b128 v[194:197], v168 offset:18432
	ds_read_b128 v[198:201], v168 offset:19456
	ds_read_b128 v[202:205], v168 offset:20480
	ds_read_b128 v[210:213], v168 offset:21504
	ds_read_b128 v[214:217], v168 offset:22528
	ds_read_b128 v[218:221], v168 offset:23552
	global_load_lds_dwordx4 v[244:245], off
	v_lshl_add_u64 v[246:247], v[206:207], 0, v[146:147]
	s_mov_b32 m0, s26
	s_nop 0
	global_load_lds_dwordx4 v[246:247], off
	s_barrier
	s_waitcnt lgkmcnt(7)
	v_mfma_f32_16x16x32_bf16 v[62:65], v[170:173], v[186:189], v[62:65]
	v_mfma_f32_16x16x32_bf16 v[58:61], v[178:181], v[186:189], v[58:61]
	s_waitcnt lgkmcnt(5)
	v_mfma_f32_16x16x32_bf16 v[54:57], v[170:173], v[194:197], v[54:57]
	v_mfma_f32_16x16x32_bf16 v[50:53], v[178:181], v[194:197], v[50:53]
	s_waitcnt lgkmcnt(3)
	v_mfma_f32_16x16x32_bf16 v[46:49], v[170:173], v[202:205], v[46:49]
	v_mfma_f32_16x16x32_bf16 v[42:45], v[178:181], v[202:205], v[42:45]
	s_waitcnt lgkmcnt(1)
	v_mfma_f32_16x16x32_bf16 v[38:41], v[170:173], v[214:217], v[38:41]
	v_mfma_f32_16x16x32_bf16 v[34:37], v[178:181], v[214:217], v[34:37]
	v_mfma_f32_16x16x32_bf16 v[62:65], v[174:177], v[190:193], v[62:65]
	v_mfma_f32_16x16x32_bf16 v[58:61], v[182:185], v[190:193], v[58:61]
	v_mfma_f32_16x16x32_bf16 v[54:57], v[174:177], v[198:201], v[54:57]
	v_mfma_f32_16x16x32_bf16 v[50:53], v[182:185], v[198:201], v[50:53]
	v_mfma_f32_16x16x32_bf16 v[46:49], v[174:177], v[210:213], v[46:49]
	v_mfma_f32_16x16x32_bf16 v[42:45], v[182:185], v[210:213], v[42:45]
	s_waitcnt lgkmcnt(0)
	v_mfma_f32_16x16x32_bf16 v[38:41], v[174:177], v[218:221], v[38:41]
	v_mfma_f32_16x16x32_bf16 v[34:37], v[182:185], v[218:221], v[34:37]
	s_barrier
	v_lshl_add_u64 v[170:171], v[164:165], 0, s[8:9]
	s_add_i32 s33, s34, s25
	v_lshl_add_u64 v[172:173], v[170:171], 0, v[138:139]
	s_mov_b32 m0, s33
	v_lshl_add_u64 v[170:171], v[170:171], 0, v[146:147]
	global_load_lds_dwordx4 v[172:173], off
	s_add_i32 m0, s33, 0x2000
	s_nop 0
	global_load_lds_dwordx4 v[170:171], off
	s_waitcnt vmcnt(6)
	s_barrier
	v_mfma_f32_16x16x32_bf16 v[30:33], v[222:225], v[186:189], v[30:33]
	v_mfma_f32_16x16x32_bf16 v[26:29], v[232:235], v[186:189], v[26:29]
	v_mfma_f32_16x16x32_bf16 v[22:25], v[222:225], v[194:197], v[22:25]
	v_mfma_f32_16x16x32_bf16 v[18:21], v[232:235], v[194:197], v[18:21]
	v_mfma_f32_16x16x32_bf16 v[14:17], v[222:225], v[202:205], v[14:17]
	v_mfma_f32_16x16x32_bf16 v[10:13], v[232:235], v[202:205], v[10:13]
	v_mfma_f32_16x16x32_bf16 v[6:9], v[222:225], v[214:217], v[6:9]
	v_mfma_f32_16x16x32_bf16 v[2:5], v[232:235], v[214:217], v[2:5]
	v_mfma_f32_16x16x32_bf16 v[30:33], v[228:231], v[190:193], v[30:33]
	v_mfma_f32_16x16x32_bf16 v[26:29], v[236:239], v[190:193], v[26:29]
	v_mfma_f32_16x16x32_bf16 v[22:25], v[228:231], v[198:201], v[22:25]
	v_mfma_f32_16x16x32_bf16 v[18:21], v[236:239], v[198:201], v[18:21]
	v_mfma_f32_16x16x32_bf16 v[14:17], v[228:231], v[210:213], v[14:17]
	v_mfma_f32_16x16x32_bf16 v[10:13], v[236:239], v[210:213], v[10:13]
	v_mfma_f32_16x16x32_bf16 v[6:9], v[228:231], v[218:221], v[6:9]
	v_mfma_f32_16x16x32_bf16 v[2:5], v[236:239], v[218:221], v[2:5]
	s_add_i32 s33, 0, 0x18000
	v_add_u32_e32 v169, s33, v167
	s_barrier
	ds_read_b128 v[170:173], v169
	ds_read_b128 v[174:177], v169 offset:1024
	ds_read_b128 v[178:181], v169 offset:2048
	ds_read_b128 v[182:185], v169 offset:3072
	v_lshl_add_u64 v[206:207], v[206:207], 0, s[8:9]
	s_mov_b32 m0, s27
	v_lshl_add_u64 v[222:223], v[206:207], 0, v[138:139]
	ds_read_b128 v[186:189], v168 offset:32768
	ds_read_b128 v[190:193], v168 offset:33792
	ds_read_b128 v[194:197], v168 offset:34816
	ds_read_b128 v[198:201], v168 offset:35840
	ds_read_b128 v[202:205], v168 offset:36864
	ds_read_b128 v[210:213], v168 offset:37888
	ds_read_b128 v[214:217], v168 offset:38912
	ds_read_b128 v[218:221], v168 offset:39936
	global_load_lds_dwordx4 v[222:223], off
	v_lshl_add_u64 v[206:207], v[206:207], 0, v[146:147]
	s_mov_b32 m0, s28
	s_nop 0
	global_load_lds_dwordx4 v[206:207], off
	s_waitcnt lgkmcnt(8)
	s_barrier
	s_waitcnt lgkmcnt(7)
	v_mfma_f32_16x16x32_bf16 v[126:129], v[170:173], v[186:189], v[126:129]
	v_mfma_f32_16x16x32_bf16 v[122:125], v[178:181], v[186:189], v[122:125]
	s_waitcnt lgkmcnt(5)
	v_mfma_f32_16x16x32_bf16 v[118:121], v[170:173], v[194:197], v[118:121]
	v_mfma_f32_16x16x32_bf16 v[114:117], v[178:181], v[194:197], v[114:117]
	s_waitcnt lgkmcnt(3)
	v_mfma_f32_16x16x32_bf16 v[110:113], v[170:173], v[202:205], v[110:113]
	v_mfma_f32_16x16x32_bf16 v[106:109], v[178:181], v[202:205], v[106:109]
	s_waitcnt lgkmcnt(1)
	v_mfma_f32_16x16x32_bf16 v[102:105], v[170:173], v[214:217], v[102:105]
	v_mfma_f32_16x16x32_bf16 v[98:101], v[178:181], v[214:217], v[98:101]
	v_mfma_f32_16x16x32_bf16 v[126:129], v[174:177], v[190:193], v[126:129]
	v_mfma_f32_16x16x32_bf16 v[122:125], v[182:185], v[190:193], v[122:125]
	v_mfma_f32_16x16x32_bf16 v[118:121], v[174:177], v[198:201], v[118:121]
	v_mfma_f32_16x16x32_bf16 v[114:117], v[182:185], v[198:201], v[114:117]
	v_mfma_f32_16x16x32_bf16 v[110:113], v[174:177], v[210:213], v[110:113]
	v_mfma_f32_16x16x32_bf16 v[106:109], v[182:185], v[210:213], v[106:109]
	s_waitcnt lgkmcnt(0)
	v_mfma_f32_16x16x32_bf16 v[102:105], v[174:177], v[218:221], v[102:105]
	v_mfma_f32_16x16x32_bf16 v[98:101], v[182:185], v[218:221], v[98:101]
	s_barrier
	s_add_i32 s34, 0, 0x1c000
	s_add_i32 s33, s33, s25
	v_add_u32_e32 v169, s34, v167
	v_lshl_add_u64 v[206:207], v[240:241], 0, s[10:11]
	s_mov_b32 m0, s33
	ds_read_b128 v[222:225], v169
	ds_read_b128 v[228:231], v169 offset:1024
	ds_read_b128 v[232:235], v169 offset:2048
	ds_read_b128 v[236:239], v169 offset:3072
	global_load_lds_dwordx4 v[206:207], off
	v_lshl_add_u64 v[206:207], v[242:243], 0, s[10:11]
	s_add_i32 m0, s33, 0x2000
	s_nop 0
	global_load_lds_dwordx4 v[206:207], off
	s_barrier
	s_waitcnt lgkmcnt(3)
	v_mfma_f32_16x16x32_bf16 v[94:97], v[222:225], v[186:189], v[94:97]
	s_waitcnt lgkmcnt(1)
	v_mfma_f32_16x16x32_bf16 v[90:93], v[232:235], v[186:189], v[90:93]
	v_mfma_f32_16x16x32_bf16 v[86:89], v[222:225], v[194:197], v[86:89]
	v_mfma_f32_16x16x32_bf16 v[82:85], v[232:235], v[194:197], v[82:85]
	v_mfma_f32_16x16x32_bf16 v[78:81], v[222:225], v[202:205], v[78:81]
	v_mfma_f32_16x16x32_bf16 v[74:77], v[232:235], v[202:205], v[74:77]
	v_mfma_f32_16x16x32_bf16 v[70:73], v[222:225], v[214:217], v[70:73]
	v_mfma_f32_16x16x32_bf16 v[66:69], v[232:235], v[214:217], v[66:69]
	v_mfma_f32_16x16x32_bf16 v[94:97], v[228:231], v[190:193], v[94:97]
	s_waitcnt lgkmcnt(0)
	v_mfma_f32_16x16x32_bf16 v[90:93], v[236:239], v[190:193], v[90:93]
	v_mfma_f32_16x16x32_bf16 v[86:89], v[228:231], v[198:201], v[86:89]
	v_mfma_f32_16x16x32_bf16 v[82:85], v[236:239], v[198:201], v[82:85]
	v_mfma_f32_16x16x32_bf16 v[78:81], v[228:231], v[210:213], v[78:81]
	v_mfma_f32_16x16x32_bf16 v[74:77], v[236:239], v[210:213], v[74:77]
	v_mfma_f32_16x16x32_bf16 v[70:73], v[228:231], v[218:221], v[70:73]
	v_mfma_f32_16x16x32_bf16 v[66:69], v[236:239], v[218:221], v[66:69]
	s_mov_b32 m0, s29
	v_lshl_add_u64 v[206:207], v[244:245], 0, s[10:11]
	s_barrier
	ds_read_b128 v[186:189], v168 offset:49152
	ds_read_b128 v[190:193], v168 offset:50176
	ds_read_b128 v[194:197], v168 offset:51200
	ds_read_b128 v[198:201], v168 offset:52224
	ds_read_b128 v[202:205], v168 offset:53248
	ds_read_b128 v[210:213], v168 offset:54272
	ds_read_b128 v[214:217], v168 offset:55296
	ds_read_b128 v[218:221], v168 offset:56320
	global_load_lds_dwordx4 v[206:207], off
	v_lshl_add_u64 v[206:207], v[246:247], 0, s[10:11]
	s_mov_b32 m0, s30
	s_nop 0
	global_load_lds_dwordx4 v[206:207], off
	s_barrier
	s_waitcnt lgkmcnt(7)
	v_mfma_f32_16x16x32_bf16 v[62:65], v[170:173], v[186:189], v[62:65]
	v_mfma_f32_16x16x32_bf16 v[58:61], v[178:181], v[186:189], v[58:61]
	s_waitcnt lgkmcnt(5)
	v_mfma_f32_16x16x32_bf16 v[54:57], v[170:173], v[194:197], v[54:57]
	v_mfma_f32_16x16x32_bf16 v[50:53], v[178:181], v[194:197], v[50:53]
	s_waitcnt lgkmcnt(3)
	v_mfma_f32_16x16x32_bf16 v[46:49], v[170:173], v[202:205], v[46:49]
	v_mfma_f32_16x16x32_bf16 v[42:45], v[178:181], v[202:205], v[42:45]
	s_waitcnt lgkmcnt(1)
	v_mfma_f32_16x16x32_bf16 v[38:41], v[170:173], v[214:217], v[38:41]
	v_mfma_f32_16x16x32_bf16 v[34:37], v[178:181], v[214:217], v[34:37]
	v_mfma_f32_16x16x32_bf16 v[62:65], v[174:177], v[190:193], v[62:65]
	v_mfma_f32_16x16x32_bf16 v[58:61], v[182:185], v[190:193], v[58:61]
	v_mfma_f32_16x16x32_bf16 v[54:57], v[174:177], v[198:201], v[54:57]
	v_mfma_f32_16x16x32_bf16 v[50:53], v[182:185], v[198:201], v[50:53]
	v_mfma_f32_16x16x32_bf16 v[46:49], v[174:177], v[210:213], v[46:49]
	v_mfma_f32_16x16x32_bf16 v[42:45], v[182:185], v[210:213], v[42:45]
	s_waitcnt lgkmcnt(0)
	v_mfma_f32_16x16x32_bf16 v[38:41], v[174:177], v[218:221], v[38:41]
	v_mfma_f32_16x16x32_bf16 v[34:37], v[182:185], v[218:221], v[34:37]
	s_barrier
	v_lshl_add_u64 v[164:165], v[164:165], 0, s[12:13]
	s_add_i32 s33, s34, s25
	v_lshl_add_u64 v[170:171], v[164:165], 0, v[138:139]
	s_mov_b32 m0, s33
	v_lshl_add_u64 v[164:165], v[164:165], 0, v[146:147]
	global_load_lds_dwordx4 v[170:171], off
	s_add_i32 m0, s33, 0x2000
	s_nop 0
	global_load_lds_dwordx4 v[164:165], off
	s_waitcnt vmcnt(6)
	s_barrier
	v_mfma_f32_16x16x32_bf16 v[30:33], v[222:225], v[186:189], v[30:33]
	v_mfma_f32_16x16x32_bf16 v[26:29], v[232:235], v[186:189], v[26:29]
	v_mfma_f32_16x16x32_bf16 v[22:25], v[222:225], v[194:197], v[22:25]
	v_mfma_f32_16x16x32_bf16 v[18:21], v[232:235], v[194:197], v[18:21]
	v_mfma_f32_16x16x32_bf16 v[14:17], v[222:225], v[202:205], v[14:17]
	v_mfma_f32_16x16x32_bf16 v[10:13], v[232:235], v[202:205], v[10:13]
	v_mfma_f32_16x16x32_bf16 v[6:9], v[222:225], v[214:217], v[6:9]
	v_mfma_f32_16x16x32_bf16 v[2:5], v[232:235], v[214:217], v[2:5]
	v_mfma_f32_16x16x32_bf16 v[30:33], v[228:231], v[190:193], v[30:33]
	v_mfma_f32_16x16x32_bf16 v[26:29], v[236:239], v[190:193], v[26:29]
	v_mfma_f32_16x16x32_bf16 v[22:25], v[228:231], v[198:201], v[22:25]
	v_mfma_f32_16x16x32_bf16 v[18:21], v[236:239], v[198:201], v[18:21]
	v_mfma_f32_16x16x32_bf16 v[14:17], v[228:231], v[210:213], v[14:17]
	v_mfma_f32_16x16x32_bf16 v[10:13], v[236:239], v[210:213], v[10:13]
	v_mfma_f32_16x16x32_bf16 v[6:9], v[228:231], v[218:221], v[6:9]
	v_mfma_f32_16x16x32_bf16 v[2:5], v[236:239], v[218:221], v[2:5]
	s_add_i32 s31, s31, 2
	s_add_u32 s6, s6, 0x100
	s_addc_u32 s7, s7, 0
	s_cmp_lt_u32 s31, 14
	s_barrier
	s_cbranch_scc1 .LBB0_1645
	s_waitcnt vmcnt(0)
	s_cmpk_gt_u32 s24, 0xff
	s_cbranch_scc1 .LBB0_1648
	s_barrier

.LBB0_1788:
	s_cmpk_eq_i32 s4, 0x700
	v_lshl_add_u64 v[170:171], v[162:163], 0, s[4:5]
	v_lshl_add_u64 v[170:171], v[170:171], 0, s[22:23]
	s_cselect_b64 vcc, -1, 0
	s_add_i32 s7, 0, 0x10000
	v_cndmask_b32_e32 v245, v171, v153, vcc
	v_add_u32_e32 v171, s7, v173
	ds_read_b128 v[176:179], v171
	ds_read_b128 v[180:183], v171 offset:1024
	ds_read_b128 v[184:187], v171 offset:2048
	ds_read_b128 v[188:191], v171 offset:3072
	v_cndmask_b32_e32 v244, v170, v152, vcc
	v_lshl_add_u64 v[170:171], v[168:169], 0, s[4:5]
	v_cndmask_b32_e32 v171, v171, v151, vcc
	v_cndmask_b32_e32 v170, v170, v150, vcc
	v_lshl_add_u64 v[228:229], v[164:165], 0, s[4:5]
	s_add_i32 m0, s34, 0xc000
	ds_read_b128 v[192:195], v174
	ds_read_b128 v[196:199], v174 offset:1024
	ds_read_b128 v[200:203], v174 offset:2048
	ds_read_b128 v[204:207], v174 offset:3072
	ds_read_b128 v[210:213], v174 offset:4096
	ds_read_b128 v[214:217], v174 offset:5120
	ds_read_b128 v[218:221], v174 offset:6144
	ds_read_b128 v[222:225], v174 offset:7168
	global_load_lds_dwordx4 v[228:229], off
	v_lshl_add_u64 v[228:229], v[166:167], 0, s[4:5]
	s_add_i32 m0, s34, 0xe000
	s_nop 0
	global_load_lds_dwordx4 v[228:229], off
	s_waitcnt lgkmcnt(8)
	s_barrier
	s_waitcnt lgkmcnt(7)
	v_mfma_f32_16x16x32_bf16 v[126:129], v[176:179], v[192:195], v[126:129]
	v_mfma_f32_16x16x32_bf16 v[122:125], v[184:187], v[192:195], v[122:125]
	s_waitcnt lgkmcnt(5)
	v_mfma_f32_16x16x32_bf16 v[118:121], v[176:179], v[200:203], v[118:121]
	v_mfma_f32_16x16x32_bf16 v[114:117], v[184:187], v[200:203], v[114:117]
	s_waitcnt lgkmcnt(3)
	v_mfma_f32_16x16x32_bf16 v[110:113], v[176:179], v[210:213], v[110:113]
	v_mfma_f32_16x16x32_bf16 v[106:109], v[184:187], v[210:213], v[106:109]
	s_waitcnt lgkmcnt(1)
	v_mfma_f32_16x16x32_bf16 v[102:105], v[176:179], v[218:221], v[102:105]
	v_mfma_f32_16x16x32_bf16 v[98:101], v[184:187], v[218:221], v[98:101]
	v_mfma_f32_16x16x32_bf16 v[126:129], v[180:183], v[196:199], v[126:129]
	v_mfma_f32_16x16x32_bf16 v[122:125], v[188:191], v[196:199], v[122:125]
	v_mfma_f32_16x16x32_bf16 v[118:121], v[180:183], v[204:207], v[118:121]
	v_mfma_f32_16x16x32_bf16 v[114:117], v[188:191], v[204:207], v[114:117]
	v_mfma_f32_16x16x32_bf16 v[110:113], v[180:183], v[214:217], v[110:113]
	v_mfma_f32_16x16x32_bf16 v[106:109], v[188:191], v[214:217], v[106:109]
	s_waitcnt lgkmcnt(0)
	v_mfma_f32_16x16x32_bf16 v[102:105], v[180:183], v[222:225], v[102:105]
	v_mfma_f32_16x16x32_bf16 v[98:101], v[188:191], v[222:225], v[98:101]
	s_barrier
	s_add_i32 s57, 0, 0x14000
	s_add_i32 s7, s7, s39
	v_add_u32_e32 v175, s57, v173
	v_lshl_add_u64 v[246:247], v[170:171], 0, v[138:139]
	s_mov_b32 m0, s7
	ds_read_b128 v[228:231], v175
	ds_read_b128 v[232:235], v175 offset:1024
	ds_read_b128 v[236:239], v175 offset:2048
	ds_read_b128 v[240:243], v175 offset:3072
	global_load_lds_dwordx4 v[246:247], off
	v_lshl_add_u64 v[248:249], v[170:171], 0, v[148:149]
	s_add_i32 m0, s7, 0x2000
	s_nop 0
	global_load_lds_dwordx4 v[248:249], off
	s_barrier
	s_waitcnt lgkmcnt(3)
	v_mfma_f32_16x16x32_bf16 v[94:97], v[228:231], v[192:195], v[94:97]
	s_waitcnt lgkmcnt(1)
	v_mfma_f32_16x16x32_bf16 v[90:93], v[236:239], v[192:195], v[90:93]
	v_mfma_f32_16x16x32_bf16 v[86:89], v[228:231], v[200:203], v[86:89]
	v_mfma_f32_16x16x32_bf16 v[82:85], v[236:239], v[200:203], v[82:85]
	v_mfma_f32_16x16x32_bf16 v[78:81], v[228:231], v[210:213], v[78:81]
	v_mfma_f32_16x16x32_bf16 v[74:77], v[236:239], v[210:213], v[74:77]
	v_mfma_f32_16x16x32_bf16 v[70:73], v[228:231], v[218:221], v[70:73]
	v_mfma_f32_16x16x32_bf16 v[66:69], v[236:239], v[218:221], v[66:69]
	v_mfma_f32_16x16x32_bf16 v[94:97], v[232:235], v[196:199], v[94:97]
	s_waitcnt lgkmcnt(0)
	v_mfma_f32_16x16x32_bf16 v[90:93], v[240:243], v[196:199], v[90:93]
	v_mfma_f32_16x16x32_bf16 v[86:89], v[232:235], v[204:207], v[86:89]
	v_mfma_f32_16x16x32_bf16 v[82:85], v[240:243], v[204:207], v[82:85]
	v_mfma_f32_16x16x32_bf16 v[78:81], v[232:235], v[214:217], v[78:81]
	v_mfma_f32_16x16x32_bf16 v[74:77], v[240:243], v[214:217], v[74:77]
	v_mfma_f32_16x16x32_bf16 v[70:73], v[232:235], v[222:225], v[70:73]
	v_mfma_f32_16x16x32_bf16 v[66:69], v[240:243], v[222:225], v[66:69]
	s_mov_b32 m0, s34
	v_lshl_add_u64 v[250:251], v[244:245], 0, v[138:139]
	s_barrier
	ds_read_b128 v[192:195], v174 offset:16384
	ds_read_b128 v[196:199], v174 offset:17408
	ds_read_b128 v[200:203], v174 offset:18432
	ds_read_b128 v[204:207], v174 offset:19456
	ds_read_b128 v[210:213], v174 offset:20480
	ds_read_b128 v[214:217], v174 offset:21504
	ds_read_b128 v[218:221], v174 offset:22528
	ds_read_b128 v[222:225], v174 offset:23552
	global_load_lds_dwordx4 v[250:251], off
	v_lshl_add_u64 v[252:253], v[244:245], 0, v[148:149]
	s_mov_b32 m0, s41
	s_nop 0
	global_load_lds_dwordx4 v[252:253], off
	s_barrier
	s_waitcnt lgkmcnt(7)
	v_mfma_f32_16x16x32_bf16 v[62:65], v[176:179], v[192:195], v[62:65]
	v_mfma_f32_16x16x32_bf16 v[58:61], v[184:187], v[192:195], v[58:61]
	s_waitcnt lgkmcnt(5)
	v_mfma_f32_16x16x32_bf16 v[54:57], v[176:179], v[200:203], v[54:57]
	v_mfma_f32_16x16x32_bf16 v[50:53], v[184:187], v[200:203], v[50:53]
	s_waitcnt lgkmcnt(3)
	v_mfma_f32_16x16x32_bf16 v[46:49], v[176:179], v[210:213], v[46:49]
	v_mfma_f32_16x16x32_bf16 v[42:45], v[184:187], v[210:213], v[42:45]
	s_waitcnt lgkmcnt(1)
	v_mfma_f32_16x16x32_bf16 v[38:41], v[176:179], v[218:221], v[38:41]
	v_mfma_f32_16x16x32_bf16 v[34:37], v[184:187], v[218:221], v[34:37]
	v_mfma_f32_16x16x32_bf16 v[62:65], v[180:183], v[196:199], v[62:65]
	v_mfma_f32_16x16x32_bf16 v[58:61], v[188:191], v[196:199], v[58:61]
	v_mfma_f32_16x16x32_bf16 v[54:57], v[180:183], v[204:207], v[54:57]
	v_mfma_f32_16x16x32_bf16 v[50:53], v[188:191], v[204:207], v[50:53]
	v_mfma_f32_16x16x32_bf16 v[46:49], v[180:183], v[214:217], v[46:49]
	v_mfma_f32_16x16x32_bf16 v[42:45], v[188:191], v[214:217], v[42:45]
	s_waitcnt lgkmcnt(0)
	v_mfma_f32_16x16x32_bf16 v[38:41], v[180:183], v[222:225], v[38:41]
	v_mfma_f32_16x16x32_bf16 v[34:37], v[188:191], v[222:225], v[34:37]
	s_barrier
	v_lshl_add_u64 v[176:177], v[170:171], 0, s[16:17]
	s_add_i32 s7, s57, s39
	v_lshl_add_u64 v[178:179], v[176:177], 0, v[138:139]
	s_mov_b32 m0, s7
	v_lshl_add_u64 v[176:177], v[176:177], 0, v[148:149]
	global_load_lds_dwordx4 v[178:179], off
	s_add_i32 m0, s7, 0x2000
	s_nop 0
	global_load_lds_dwordx4 v[176:177], off
	s_waitcnt vmcnt(6)
	s_barrier
	v_mfma_f32_16x16x32_bf16 v[30:33], v[228:231], v[192:195], v[30:33]
	v_mfma_f32_16x16x32_bf16 v[26:29], v[236:239], v[192:195], v[26:29]
	v_mfma_f32_16x16x32_bf16 v[22:25], v[228:231], v[200:203], v[22:25]
	v_mfma_f32_16x16x32_bf16 v[18:21], v[236:239], v[200:203], v[18:21]
	v_mfma_f32_16x16x32_bf16 v[14:17], v[228:231], v[210:213], v[14:17]
	v_mfma_f32_16x16x32_bf16 v[10:13], v[236:239], v[210:213], v[10:13]
	v_mfma_f32_16x16x32_bf16 v[6:9], v[228:231], v[218:221], v[6:9]
	v_mfma_f32_16x16x32_bf16 v[2:5], v[236:239], v[218:221], v[2:5]
	v_mfma_f32_16x16x32_bf16 v[30:33], v[232:235], v[196:199], v[30:33]
	v_mfma_f32_16x16x32_bf16 v[26:29], v[240:243], v[196:199], v[26:29]
	v_mfma_f32_16x16x32_bf16 v[22:25], v[232:235], v[204:207], v[22:25]
	v_mfma_f32_16x16x32_bf16 v[18:21], v[240:243], v[204:207], v[18:21]
	v_mfma_f32_16x16x32_bf16 v[14:17], v[232:235], v[214:217], v[14:17]
	v_mfma_f32_16x16x32_bf16 v[10:13], v[240:243], v[214:217], v[10:13]
	v_mfma_f32_16x16x32_bf16 v[6:9], v[232:235], v[222:225], v[6:9]
	v_mfma_f32_16x16x32_bf16 v[2:5], v[240:243], v[222:225], v[2:5]
	s_add_i32 s7, 0, 0x18000
	v_add_u32_e32 v175, s7, v173
	s_barrier
	ds_read_b128 v[176:179], v175
	ds_read_b128 v[180:183], v175 offset:1024
	ds_read_b128 v[184:187], v175 offset:2048
	ds_read_b128 v[188:191], v175 offset:3072
	v_lshl_add_u64 v[228:229], v[244:245], 0, s[16:17]
	s_mov_b32 m0, s42
	v_lshl_add_u64 v[230:231], v[228:229], 0, v[138:139]
	ds_read_b128 v[192:195], v174 offset:32768
	ds_read_b128 v[196:199], v174 offset:33792
	ds_read_b128 v[200:203], v174 offset:34816
	ds_read_b128 v[204:207], v174 offset:35840
	ds_read_b128 v[210:213], v174 offset:36864
	ds_read_b128 v[214:217], v174 offset:37888
	ds_read_b128 v[218:221], v174 offset:38912
	ds_read_b128 v[222:225], v174 offset:39936
	global_load_lds_dwordx4 v[230:231], off
	v_lshl_add_u64 v[228:229], v[228:229], 0, v[148:149]
	s_mov_b32 m0, s43
	s_nop 0
	global_load_lds_dwordx4 v[228:229], off
	s_waitcnt lgkmcnt(8)
	s_barrier
	s_waitcnt lgkmcnt(7)
	v_mfma_f32_16x16x32_bf16 v[126:129], v[176:179], v[192:195], v[126:129]
	v_mfma_f32_16x16x32_bf16 v[122:125], v[184:187], v[192:195], v[122:125]
	s_waitcnt lgkmcnt(5)
	v_mfma_f32_16x16x32_bf16 v[118:121], v[176:179], v[200:203], v[118:121]
	v_mfma_f32_16x16x32_bf16 v[114:117], v[184:187], v[200:203], v[114:117]
	s_waitcnt lgkmcnt(3)
	v_mfma_f32_16x16x32_bf16 v[110:113], v[176:179], v[210:213], v[110:113]
	v_mfma_f32_16x16x32_bf16 v[106:109], v[184:187], v[210:213], v[106:109]
	s_waitcnt lgkmcnt(1)
	v_mfma_f32_16x16x32_bf16 v[102:105], v[176:179], v[218:221], v[102:105]
	v_mfma_f32_16x16x32_bf16 v[98:101], v[184:187], v[218:221], v[98:101]
	v_mfma_f32_16x16x32_bf16 v[126:129], v[180:183], v[196:199], v[126:129]
	v_mfma_f32_16x16x32_bf16 v[122:125], v[188:191], v[196:199], v[122:125]
	v_mfma_f32_16x16x32_bf16 v[118:121], v[180:183], v[204:207], v[118:121]
	v_mfma_f32_16x16x32_bf16 v[114:117], v[188:191], v[204:207], v[114:117]
	v_mfma_f32_16x16x32_bf16 v[110:113], v[180:183], v[214:217], v[110:113]
	v_mfma_f32_16x16x32_bf16 v[106:109], v[188:191], v[214:217], v[106:109]
	s_waitcnt lgkmcnt(0)
	v_mfma_f32_16x16x32_bf16 v[102:105], v[180:183], v[222:225], v[102:105]
	v_mfma_f32_16x16x32_bf16 v[98:101], v[188:191], v[222:225], v[98:101]
	s_barrier
	s_add_i32 s57, 0, 0x1c000
	s_add_i32 s7, s7, s39
	v_add_u32_e32 v175, s57, v173
	v_lshl_add_u64 v[244:245], v[246:247], 0, s[18:19]
	s_mov_b32 m0, s7
	ds_read_b128 v[228:231], v175
	ds_read_b128 v[232:235], v175 offset:1024
	ds_read_b128 v[236:239], v175 offset:2048
	ds_read_b128 v[240:243], v175 offset:3072
	global_load_lds_dwordx4 v[244:245], off
	v_lshl_add_u64 v[244:245], v[248:249], 0, s[18:19]
	s_add_i32 m0, s7, 0x2000
	s_nop 0
	global_load_lds_dwordx4 v[244:245], off
	s_barrier
	s_waitcnt lgkmcnt(3)
	v_mfma_f32_16x16x32_bf16 v[94:97], v[228:231], v[192:195], v[94:97]
	s_waitcnt lgkmcnt(1)
	v_mfma_f32_16x16x32_bf16 v[90:93], v[236:239], v[192:195], v[90:93]
	v_mfma_f32_16x16x32_bf16 v[86:89], v[228:231], v[200:203], v[86:89]
	v_mfma_f32_16x16x32_bf16 v[82:85], v[236:239], v[200:203], v[82:85]
	v_mfma_f32_16x16x32_bf16 v[78:81], v[228:231], v[210:213], v[78:81]
	v_mfma_f32_16x16x32_bf16 v[74:77], v[236:239], v[210:213], v[74:77]
	v_mfma_f32_16x16x32_bf16 v[70:73], v[228:231], v[218:221], v[70:73]
	v_mfma_f32_16x16x32_bf16 v[66:69], v[236:239], v[218:221], v[66:69]
	v_mfma_f32_16x16x32_bf16 v[94:97], v[232:235], v[196:199], v[94:97]
	s_waitcnt lgkmcnt(0)
	v_mfma_f32_16x16x32_bf16 v[90:93], v[240:243], v[196:199], v[90:93]
	v_mfma_f32_16x16x32_bf16 v[86:89], v[232:235], v[204:207], v[86:89]
	v_mfma_f32_16x16x32_bf16 v[82:85], v[240:243], v[204:207], v[82:85]
	v_mfma_f32_16x16x32_bf16 v[78:81], v[232:235], v[214:217], v[78:81]
	v_mfma_f32_16x16x32_bf16 v[74:77], v[240:243], v[214:217], v[74:77]
	v_mfma_f32_16x16x32_bf16 v[70:73], v[232:235], v[222:225], v[70:73]
	v_mfma_f32_16x16x32_bf16 v[66:69], v[240:243], v[222:225], v[66:69]
	s_mov_b32 m0, s55
	v_lshl_add_u64 v[244:245], v[250:251], 0, s[18:19]
	s_barrier
	ds_read_b128 v[192:195], v174 offset:49152
	ds_read_b128 v[196:199], v174 offset:50176
	ds_read_b128 v[200:203], v174 offset:51200
	ds_read_b128 v[204:207], v174 offset:52224
	ds_read_b128 v[210:213], v174 offset:53248
	ds_read_b128 v[214:217], v174 offset:54272
	ds_read_b128 v[218:221], v174 offset:55296
	ds_read_b128 v[222:225], v174 offset:56320
	global_load_lds_dwordx4 v[244:245], off
	v_lshl_add_u64 v[244:245], v[252:253], 0, s[18:19]
	s_mov_b32 m0, s56
	s_nop 0
	global_load_lds_dwordx4 v[244:245], off
	s_barrier
	s_waitcnt lgkmcnt(7)
	v_mfma_f32_16x16x32_bf16 v[62:65], v[176:179], v[192:195], v[62:65]
	v_mfma_f32_16x16x32_bf16 v[58:61], v[184:187], v[192:195], v[58:61]
	s_waitcnt lgkmcnt(5)
	v_mfma_f32_16x16x32_bf16 v[54:57], v[176:179], v[200:203], v[54:57]
	v_mfma_f32_16x16x32_bf16 v[50:53], v[184:187], v[200:203], v[50:53]
	s_waitcnt lgkmcnt(3)
	v_mfma_f32_16x16x32_bf16 v[46:49], v[176:179], v[210:213], v[46:49]
	v_mfma_f32_16x16x32_bf16 v[42:45], v[184:187], v[210:213], v[42:45]
	s_waitcnt lgkmcnt(1)
	v_mfma_f32_16x16x32_bf16 v[38:41], v[176:179], v[218:221], v[38:41]
	v_mfma_f32_16x16x32_bf16 v[34:37], v[184:187], v[218:221], v[34:37]
	v_mfma_f32_16x16x32_bf16 v[62:65], v[180:183], v[196:199], v[62:65]
	v_mfma_f32_16x16x32_bf16 v[58:61], v[188:191], v[196:199], v[58:61]
	v_mfma_f32_16x16x32_bf16 v[54:57], v[180:183], v[204:207], v[54:57]
	v_mfma_f32_16x16x32_bf16 v[50:53], v[188:191], v[204:207], v[50:53]
	v_mfma_f32_16x16x32_bf16 v[46:49], v[180:183], v[214:217], v[46:49]
	v_mfma_f32_16x16x32_bf16 v[42:45], v[188:191], v[214:217], v[42:45]
	s_waitcnt lgkmcnt(0)
	v_mfma_f32_16x16x32_bf16 v[38:41], v[180:183], v[222:225], v[38:41]
	v_mfma_f32_16x16x32_bf16 v[34:37], v[188:191], v[222:225], v[34:37]
	s_barrier
	v_lshl_add_u64 v[170:171], v[170:171], 0, s[20:21]
	s_add_i32 s7, s57, s39
	v_lshl_add_u64 v[176:177], v[170:171], 0, v[138:139]
	s_mov_b32 m0, s7
	v_lshl_add_u64 v[170:171], v[170:171], 0, v[148:149]
	global_load_lds_dwordx4 v[176:177], off
	s_add_i32 m0, s7, 0x2000
	s_nop 0
	global_load_lds_dwordx4 v[170:171], off
	s_waitcnt vmcnt(6)
	s_barrier
	v_mfma_f32_16x16x32_bf16 v[30:33], v[228:231], v[192:195], v[30:33]
	v_mfma_f32_16x16x32_bf16 v[26:29], v[236:239], v[192:195], v[26:29]
	v_mfma_f32_16x16x32_bf16 v[22:25], v[228:231], v[200:203], v[22:25]
	v_mfma_f32_16x16x32_bf16 v[18:21], v[236:239], v[200:203], v[18:21]
	v_mfma_f32_16x16x32_bf16 v[14:17], v[228:231], v[210:213], v[14:17]
	v_mfma_f32_16x16x32_bf16 v[10:13], v[236:239], v[210:213], v[10:13]
	v_mfma_f32_16x16x32_bf16 v[6:9], v[228:231], v[218:221], v[6:9]
	v_mfma_f32_16x16x32_bf16 v[2:5], v[236:239], v[218:221], v[2:5]
	v_mfma_f32_16x16x32_bf16 v[30:33], v[232:235], v[196:199], v[30:33]
	v_mfma_f32_16x16x32_bf16 v[26:29], v[240:243], v[196:199], v[26:29]
	v_mfma_f32_16x16x32_bf16 v[22:25], v[232:235], v[204:207], v[22:25]
	v_mfma_f32_16x16x32_bf16 v[18:21], v[240:243], v[204:207], v[18:21]
	v_mfma_f32_16x16x32_bf16 v[14:17], v[232:235], v[214:217], v[14:17]
	v_mfma_f32_16x16x32_bf16 v[10:13], v[240:243], v[214:217], v[10:13]
	v_mfma_f32_16x16x32_bf16 v[6:9], v[232:235], v[222:225], v[6:9]
	v_mfma_f32_16x16x32_bf16 v[2:5], v[240:243], v[222:225], v[2:5]
	s_add_i32 s6, s6, 2
	s_add_u32 s4, s4, 0x100
	s_addc_u32 s5, s5, 0
	s_cmp_lt_u32 s6, 14
	s_barrier
	s_cbranch_scc1 .LBB0_1788
	s_waitcnt vmcnt(0)
	s_cmpk_gt_u32 s38, 0xff
	s_cbranch_scc1 .LBB0_1791
	s_barrier

.LBB0_1914:
	s_add_u32 s38, s4, 0xf8cd0080
	s_addc_u32 s39, s5, -1
	s_cmp_lg_u32 s37, 40
	s_cselect_b32 s39, s39, 0
	s_cselect_b32 s38, s38, 0
	s_add_i32 s40, 0, 0x10000
	v_add_u32_e32 v156, s40, v162
	ds_read_b128 v[164:167], v156
	ds_read_b128 v[168:171], v156 offset:1024
	ds_read_b128 v[172:175], v156 offset:2048
	ds_read_b128 v[176:179], v156 offset:3072
	v_lshl_add_u64 v[232:233], v[148:149], 0, s[38:39]
	v_lshl_add_u64 v[156:157], v[146:147], 0, s[38:39]
	v_lshl_add_u64 v[214:215], v[150:151], 0, s[4:5]
	s_add_i32 m0, s28, 0xc000
	ds_read_b128 v[180:183], v163
	ds_read_b128 v[184:187], v163 offset:1024
	ds_read_b128 v[188:191], v163 offset:2048
	ds_read_b128 v[192:195], v163 offset:3072
	ds_read_b128 v[196:199], v163 offset:4096
	ds_read_b128 v[200:203], v163 offset:5120
	ds_read_b128 v[204:207], v163 offset:6144
	ds_read_b128 v[210:213], v163 offset:7168
	global_load_lds_dwordx4 v[214:215], off
	v_lshl_add_u64 v[214:215], v[152:153], 0, s[4:5]
	s_add_i32 m0, s28, 0xe000
	s_nop 0
	global_load_lds_dwordx4 v[214:215], off
	s_waitcnt lgkmcnt(8)
	s_barrier
	s_waitcnt lgkmcnt(7)
	v_mfma_f32_16x16x32_bf16 v[126:129], v[164:167], v[180:183], v[126:129]
	v_mfma_f32_16x16x32_bf16 v[122:125], v[172:175], v[180:183], v[122:125]
	s_waitcnt lgkmcnt(5)
	v_mfma_f32_16x16x32_bf16 v[118:121], v[164:167], v[188:191], v[118:121]
	v_mfma_f32_16x16x32_bf16 v[114:117], v[172:175], v[188:191], v[114:117]
	s_waitcnt lgkmcnt(3)
	v_mfma_f32_16x16x32_bf16 v[110:113], v[164:167], v[196:199], v[110:113]
	v_mfma_f32_16x16x32_bf16 v[106:109], v[172:175], v[196:199], v[106:109]
	s_waitcnt lgkmcnt(1)
	v_mfma_f32_16x16x32_bf16 v[102:105], v[164:167], v[204:207], v[102:105]
	v_mfma_f32_16x16x32_bf16 v[98:101], v[172:175], v[204:207], v[98:101]
	v_mfma_f32_16x16x32_bf16 v[126:129], v[168:171], v[184:187], v[126:129]
	v_mfma_f32_16x16x32_bf16 v[122:125], v[176:179], v[184:187], v[122:125]
	v_mfma_f32_16x16x32_bf16 v[118:121], v[168:171], v[192:195], v[118:121]
	v_mfma_f32_16x16x32_bf16 v[114:117], v[176:179], v[192:195], v[114:117]
	v_mfma_f32_16x16x32_bf16 v[110:113], v[168:171], v[200:203], v[110:113]
	v_mfma_f32_16x16x32_bf16 v[106:109], v[176:179], v[200:203], v[106:109]
	s_waitcnt lgkmcnt(0)
	v_mfma_f32_16x16x32_bf16 v[102:105], v[168:171], v[210:213], v[102:105]
	v_mfma_f32_16x16x32_bf16 v[98:101], v[176:179], v[210:213], v[98:101]
	s_barrier
	s_add_i32 s38, 0, 0x14000
	s_add_i32 s39, s40, s27
	v_add_u32_e32 v208, s38, v162
	v_lshl_add_u64 v[234:235], v[156:157], 0, v[130:131]
	s_mov_b32 m0, s39
	ds_read_b128 v[214:217], v208
	ds_read_b128 v[218:221], v208 offset:1024
	ds_read_b128 v[222:225], v208 offset:2048
	ds_read_b128 v[228:231], v208 offset:3072
	global_load_lds_dwordx4 v[234:235], off
	v_lshl_add_u64 v[236:237], v[156:157], 0, v[144:145]
	s_add_i32 m0, s39, 0x2000
	s_nop 0
	global_load_lds_dwordx4 v[236:237], off
	s_barrier
	s_waitcnt lgkmcnt(3)
	v_mfma_f32_16x16x32_bf16 v[94:97], v[214:217], v[180:183], v[94:97]
	s_waitcnt lgkmcnt(1)
	v_mfma_f32_16x16x32_bf16 v[90:93], v[222:225], v[180:183], v[90:93]
	v_mfma_f32_16x16x32_bf16 v[86:89], v[214:217], v[188:191], v[86:89]
	v_mfma_f32_16x16x32_bf16 v[82:85], v[222:225], v[188:191], v[82:85]
	v_mfma_f32_16x16x32_bf16 v[78:81], v[214:217], v[196:199], v[78:81]
	v_mfma_f32_16x16x32_bf16 v[74:77], v[222:225], v[196:199], v[74:77]
	v_mfma_f32_16x16x32_bf16 v[70:73], v[214:217], v[204:207], v[70:73]
	v_mfma_f32_16x16x32_bf16 v[66:69], v[222:225], v[204:207], v[66:69]
	v_mfma_f32_16x16x32_bf16 v[94:97], v[218:221], v[184:187], v[94:97]
	s_waitcnt lgkmcnt(0)
	v_mfma_f32_16x16x32_bf16 v[90:93], v[228:231], v[184:187], v[90:93]
	v_mfma_f32_16x16x32_bf16 v[86:89], v[218:221], v[192:195], v[86:89]
	v_mfma_f32_16x16x32_bf16 v[82:85], v[228:231], v[192:195], v[82:85]
	v_mfma_f32_16x16x32_bf16 v[78:81], v[218:221], v[200:203], v[78:81]
	v_mfma_f32_16x16x32_bf16 v[74:77], v[228:231], v[200:203], v[74:77]
	v_mfma_f32_16x16x32_bf16 v[70:73], v[218:221], v[210:213], v[70:73]
	v_mfma_f32_16x16x32_bf16 v[66:69], v[228:231], v[210:213], v[66:69]
	s_mov_b32 m0, s28
	v_lshl_add_u64 v[238:239], v[232:233], 0, v[130:131]
	s_barrier
	ds_read_b128 v[180:183], v163 offset:16384
	ds_read_b128 v[184:187], v163 offset:17408
	ds_read_b128 v[188:191], v163 offset:18432
	ds_read_b128 v[192:195], v163 offset:19456
	ds_read_b128 v[196:199], v163 offset:20480
	ds_read_b128 v[200:203], v163 offset:21504
	ds_read_b128 v[204:207], v163 offset:22528
	ds_read_b128 v[210:213], v163 offset:23552
	global_load_lds_dwordx4 v[238:239], off
	v_lshl_add_u64 v[240:241], v[232:233], 0, v[144:145]
	s_mov_b32 m0, s29
	s_nop 0
	global_load_lds_dwordx4 v[240:241], off
	s_barrier
	s_waitcnt lgkmcnt(7)
	v_mfma_f32_16x16x32_bf16 v[62:65], v[164:167], v[180:183], v[62:65]
	v_mfma_f32_16x16x32_bf16 v[58:61], v[172:175], v[180:183], v[58:61]
	s_waitcnt lgkmcnt(5)
	v_mfma_f32_16x16x32_bf16 v[54:57], v[164:167], v[188:191], v[54:57]
	v_mfma_f32_16x16x32_bf16 v[50:53], v[172:175], v[188:191], v[50:53]
	s_waitcnt lgkmcnt(3)
	v_mfma_f32_16x16x32_bf16 v[46:49], v[164:167], v[196:199], v[46:49]
	v_mfma_f32_16x16x32_bf16 v[42:45], v[172:175], v[196:199], v[42:45]
	s_waitcnt lgkmcnt(1)
	v_mfma_f32_16x16x32_bf16 v[38:41], v[164:167], v[204:207], v[38:41]
	v_mfma_f32_16x16x32_bf16 v[34:37], v[172:175], v[204:207], v[34:37]
	v_mfma_f32_16x16x32_bf16 v[62:65], v[168:171], v[184:187], v[62:65]
	v_mfma_f32_16x16x32_bf16 v[58:61], v[176:179], v[184:187], v[58:61]
	v_mfma_f32_16x16x32_bf16 v[54:57], v[168:171], v[192:195], v[54:57]
	v_mfma_f32_16x16x32_bf16 v[50:53], v[176:179], v[192:195], v[50:53]
	v_mfma_f32_16x16x32_bf16 v[46:49], v[168:171], v[200:203], v[46:49]
	v_mfma_f32_16x16x32_bf16 v[42:45], v[176:179], v[200:203], v[42:45]
	s_waitcnt lgkmcnt(0)
	v_mfma_f32_16x16x32_bf16 v[38:41], v[168:171], v[210:213], v[38:41]
	v_mfma_f32_16x16x32_bf16 v[34:37], v[176:179], v[210:213], v[34:37]
	s_barrier
	v_lshl_add_u64 v[164:165], v[156:157], 0, s[16:17]
	s_add_i32 s38, s38, s27
	v_lshl_add_u64 v[166:167], v[164:165], 0, v[130:131]
	s_mov_b32 m0, s38
	v_lshl_add_u64 v[164:165], v[164:165], 0, v[144:145]
	global_load_lds_dwordx4 v[166:167], off
	s_add_i32 m0, s38, 0x2000
	s_nop 0
	global_load_lds_dwordx4 v[164:165], off
	s_waitcnt vmcnt(6)
	s_barrier
	v_mfma_f32_16x16x32_bf16 v[30:33], v[214:217], v[180:183], v[30:33]
	v_mfma_f32_16x16x32_bf16 v[26:29], v[222:225], v[180:183], v[26:29]
	v_mfma_f32_16x16x32_bf16 v[22:25], v[214:217], v[188:191], v[22:25]
	v_mfma_f32_16x16x32_bf16 v[18:21], v[222:225], v[188:191], v[18:21]
	v_mfma_f32_16x16x32_bf16 v[14:17], v[214:217], v[196:199], v[14:17]
	v_mfma_f32_16x16x32_bf16 v[10:13], v[222:225], v[196:199], v[10:13]
	v_mfma_f32_16x16x32_bf16 v[6:9], v[214:217], v[204:207], v[6:9]
	v_mfma_f32_16x16x32_bf16 v[2:5], v[222:225], v[204:207], v[2:5]
	v_mfma_f32_16x16x32_bf16 v[30:33], v[218:221], v[184:187], v[30:33]
	v_mfma_f32_16x16x32_bf16 v[26:29], v[228:231], v[184:187], v[26:29]
	v_mfma_f32_16x16x32_bf16 v[22:25], v[218:221], v[192:195], v[22:25]
	v_mfma_f32_16x16x32_bf16 v[18:21], v[228:231], v[192:195], v[18:21]
	v_mfma_f32_16x16x32_bf16 v[14:17], v[218:221], v[200:203], v[14:17]
	v_mfma_f32_16x16x32_bf16 v[10:13], v[228:231], v[200:203], v[10:13]
	v_mfma_f32_16x16x32_bf16 v[6:9], v[218:221], v[210:213], v[6:9]
	v_mfma_f32_16x16x32_bf16 v[2:5], v[228:231], v[210:213], v[2:5]
	s_add_i32 s38, 0, 0x18000
	v_add_u32_e32 v176, s38, v162
	s_barrier
	ds_read_b128 v[164:167], v176
	ds_read_b128 v[168:171], v176 offset:1024
	ds_read_b128 v[172:175], v176 offset:2048
	ds_read_b128 v[176:179], v176 offset:3072
	v_lshl_add_u64 v[214:215], v[232:233], 0, s[16:17]
	s_mov_b32 m0, s31
	v_lshl_add_u64 v[216:217], v[214:215], 0, v[130:131]
	ds_read_b128 v[180:183], v163 offset:32768
	ds_read_b128 v[184:187], v163 offset:33792
	ds_read_b128 v[188:191], v163 offset:34816
	ds_read_b128 v[192:195], v163 offset:35840
	ds_read_b128 v[196:199], v163 offset:36864
	ds_read_b128 v[200:203], v163 offset:37888
	ds_read_b128 v[204:207], v163 offset:38912
	ds_read_b128 v[210:213], v163 offset:39936
	global_load_lds_dwordx4 v[216:217], off
	v_lshl_add_u64 v[214:215], v[214:215], 0, v[144:145]
	s_mov_b32 m0, s34
	s_nop 0
	global_load_lds_dwordx4 v[214:215], off
	s_waitcnt lgkmcnt(8)
	s_barrier
	s_waitcnt lgkmcnt(7)
	v_mfma_f32_16x16x32_bf16 v[126:129], v[164:167], v[180:183], v[126:129]
	v_mfma_f32_16x16x32_bf16 v[122:125], v[172:175], v[180:183], v[122:125]
	s_waitcnt lgkmcnt(5)
	v_mfma_f32_16x16x32_bf16 v[118:121], v[164:167], v[188:191], v[118:121]
	v_mfma_f32_16x16x32_bf16 v[114:117], v[172:175], v[188:191], v[114:117]
	s_waitcnt lgkmcnt(3)
	v_mfma_f32_16x16x32_bf16 v[110:113], v[164:167], v[196:199], v[110:113]
	v_mfma_f32_16x16x32_bf16 v[106:109], v[172:175], v[196:199], v[106:109]
	s_waitcnt lgkmcnt(1)
	v_mfma_f32_16x16x32_bf16 v[102:105], v[164:167], v[204:207], v[102:105]
	v_mfma_f32_16x16x32_bf16 v[98:101], v[172:175], v[204:207], v[98:101]
	v_mfma_f32_16x16x32_bf16 v[126:129], v[168:171], v[184:187], v[126:129]
	v_mfma_f32_16x16x32_bf16 v[122:125], v[176:179], v[184:187], v[122:125]
	v_mfma_f32_16x16x32_bf16 v[118:121], v[168:171], v[192:195], v[118:121]
	v_mfma_f32_16x16x32_bf16 v[114:117], v[176:179], v[192:195], v[114:117]
	v_mfma_f32_16x16x32_bf16 v[110:113], v[168:171], v[200:203], v[110:113]
	v_mfma_f32_16x16x32_bf16 v[106:109], v[176:179], v[200:203], v[106:109]
	s_waitcnt lgkmcnt(0)
	v_mfma_f32_16x16x32_bf16 v[102:105], v[168:171], v[210:213], v[102:105]
	v_mfma_f32_16x16x32_bf16 v[98:101], v[176:179], v[210:213], v[98:101]
	s_barrier
	s_add_i32 s39, 0, 0x1c000
	s_add_i32 s38, s38, s27
	v_add_u32_e32 v208, s39, v162
	v_lshl_add_u64 v[232:233], v[234:235], 0, s[18:19]
	s_mov_b32 m0, s38
	ds_read_b128 v[214:217], v208
	ds_read_b128 v[218:221], v208 offset:1024
	ds_read_b128 v[222:225], v208 offset:2048
	ds_read_b128 v[228:231], v208 offset:3072
	global_load_lds_dwordx4 v[232:233], off
	v_lshl_add_u64 v[232:233], v[236:237], 0, s[18:19]
	s_add_i32 m0, s38, 0x2000
	s_nop 0
	global_load_lds_dwordx4 v[232:233], off
	s_barrier
	s_waitcnt lgkmcnt(3)
	v_mfma_f32_16x16x32_bf16 v[94:97], v[214:217], v[180:183], v[94:97]
	s_waitcnt lgkmcnt(1)
	v_mfma_f32_16x16x32_bf16 v[90:93], v[222:225], v[180:183], v[90:93]
	v_mfma_f32_16x16x32_bf16 v[86:89], v[214:217], v[188:191], v[86:89]
	v_mfma_f32_16x16x32_bf16 v[82:85], v[222:225], v[188:191], v[82:85]
	v_mfma_f32_16x16x32_bf16 v[78:81], v[214:217], v[196:199], v[78:81]
	v_mfma_f32_16x16x32_bf16 v[74:77], v[222:225], v[196:199], v[74:77]
	v_mfma_f32_16x16x32_bf16 v[70:73], v[214:217], v[204:207], v[70:73]
	v_mfma_f32_16x16x32_bf16 v[66:69], v[222:225], v[204:207], v[66:69]
	v_mfma_f32_16x16x32_bf16 v[94:97], v[218:221], v[184:187], v[94:97]
	s_waitcnt lgkmcnt(0)
	v_mfma_f32_16x16x32_bf16 v[90:93], v[228:231], v[184:187], v[90:93]
	v_mfma_f32_16x16x32_bf16 v[86:89], v[218:221], v[192:195], v[86:89]
	v_mfma_f32_16x16x32_bf16 v[82:85], v[228:231], v[192:195], v[82:85]
	v_mfma_f32_16x16x32_bf16 v[78:81], v[218:221], v[200:203], v[78:81]
	v_mfma_f32_16x16x32_bf16 v[74:77], v[228:231], v[200:203], v[74:77]
	v_mfma_f32_16x16x32_bf16 v[70:73], v[218:221], v[210:213], v[70:73]
	v_mfma_f32_16x16x32_bf16 v[66:69], v[228:231], v[210:213], v[66:69]
	s_mov_b32 m0, s35
	v_lshl_add_u64 v[232:233], v[238:239], 0, s[18:19]
	s_barrier
	ds_read_b128 v[180:183], v163 offset:49152
	ds_read_b128 v[184:187], v163 offset:50176
	ds_read_b128 v[188:191], v163 offset:51200
	ds_read_b128 v[192:195], v163 offset:52224
	ds_read_b128 v[196:199], v163 offset:53248
	ds_read_b128 v[200:203], v163 offset:54272
	ds_read_b128 v[204:207], v163 offset:55296
	ds_read_b128 v[210:213], v163 offset:56320
	global_load_lds_dwordx4 v[232:233], off
	v_lshl_add_u64 v[232:233], v[240:241], 0, s[18:19]
	s_mov_b32 m0, s36
	s_nop 0
	global_load_lds_dwordx4 v[232:233], off
	s_barrier
	s_waitcnt lgkmcnt(7)
	v_mfma_f32_16x16x32_bf16 v[62:65], v[164:167], v[180:183], v[62:65]
	v_mfma_f32_16x16x32_bf16 v[58:61], v[172:175], v[180:183], v[58:61]
	s_waitcnt lgkmcnt(5)
	v_mfma_f32_16x16x32_bf16 v[54:57], v[164:167], v[188:191], v[54:57]
	v_mfma_f32_16x16x32_bf16 v[50:53], v[172:175], v[188:191], v[50:53]
	s_waitcnt lgkmcnt(3)
	v_mfma_f32_16x16x32_bf16 v[46:49], v[164:167], v[196:199], v[46:49]
	v_mfma_f32_16x16x32_bf16 v[42:45], v[172:175], v[196:199], v[42:45]
	s_waitcnt lgkmcnt(1)
	v_mfma_f32_16x16x32_bf16 v[38:41], v[164:167], v[204:207], v[38:41]
	v_mfma_f32_16x16x32_bf16 v[34:37], v[172:175], v[204:207], v[34:37]
	v_mfma_f32_16x16x32_bf16 v[62:65], v[168:171], v[184:187], v[62:65]
	v_mfma_f32_16x16x32_bf16 v[58:61], v[176:179], v[184:187], v[58:61]
	v_mfma_f32_16x16x32_bf16 v[54:57], v[168:171], v[192:195], v[54:57]
	v_mfma_f32_16x16x32_bf16 v[50:53], v[176:179], v[192:195], v[50:53]
	v_mfma_f32_16x16x32_bf16 v[46:49], v[168:171], v[200:203], v[46:49]
	v_mfma_f32_16x16x32_bf16 v[42:45], v[176:179], v[200:203], v[42:45]
	s_waitcnt lgkmcnt(0)
	v_mfma_f32_16x16x32_bf16 v[38:41], v[168:171], v[210:213], v[38:41]
	v_mfma_f32_16x16x32_bf16 v[34:37], v[176:179], v[210:213], v[34:37]
	s_barrier
	v_lshl_add_u64 v[156:157], v[156:157], 0, s[20:21]
	s_add_i32 s38, s39, s27
	v_lshl_add_u64 v[164:165], v[156:157], 0, v[130:131]
	s_mov_b32 m0, s38
	v_lshl_add_u64 v[156:157], v[156:157], 0, v[144:145]
	global_load_lds_dwordx4 v[164:165], off
	s_add_i32 m0, s38, 0x2000
	s_nop 0
	global_load_lds_dwordx4 v[156:157], off
	s_waitcnt vmcnt(6)
	s_barrier
	v_mfma_f32_16x16x32_bf16 v[30:33], v[214:217], v[180:183], v[30:33]
	v_mfma_f32_16x16x32_bf16 v[26:29], v[222:225], v[180:183], v[26:29]
	v_mfma_f32_16x16x32_bf16 v[22:25], v[214:217], v[188:191], v[22:25]
	v_mfma_f32_16x16x32_bf16 v[18:21], v[222:225], v[188:191], v[18:21]
	v_mfma_f32_16x16x32_bf16 v[14:17], v[214:217], v[196:199], v[14:17]
	v_mfma_f32_16x16x32_bf16 v[10:13], v[222:225], v[196:199], v[10:13]
	v_mfma_f32_16x16x32_bf16 v[6:9], v[214:217], v[204:207], v[6:9]
	v_mfma_f32_16x16x32_bf16 v[2:5], v[222:225], v[204:207], v[2:5]
	v_mfma_f32_16x16x32_bf16 v[30:33], v[218:221], v[184:187], v[30:33]
	v_mfma_f32_16x16x32_bf16 v[26:29], v[228:231], v[184:187], v[26:29]
	v_mfma_f32_16x16x32_bf16 v[22:25], v[218:221], v[192:195], v[22:25]
	v_mfma_f32_16x16x32_bf16 v[18:21], v[228:231], v[192:195], v[18:21]
	v_mfma_f32_16x16x32_bf16 v[14:17], v[218:221], v[200:203], v[14:17]
	v_mfma_f32_16x16x32_bf16 v[10:13], v[228:231], v[200:203], v[10:13]
	v_mfma_f32_16x16x32_bf16 v[6:9], v[218:221], v[210:213], v[6:9]
	v_mfma_f32_16x16x32_bf16 v[2:5], v[228:231], v[210:213], v[2:5]
	s_add_i32 s37, s37, 2
	s_add_u32 s4, s4, 0x100
	s_addc_u32 s5, s5, 0
	s_cmp_lt_u32 s37, 42
	s_barrier
	s_cbranch_scc1 .LBB0_1914
	s_waitcnt vmcnt(0)
	s_cmpk_gt_u32 s26, 0xff
	s_cbranch_scc1 .LBB0_1917
	s_barrier
